# UP GEMM epilogue hand-rewritten: A rows permuted so a lane holds 4 consecutive rows, conv via same-lane neighbours + DPP at lane edges, dwordx4 act stores
# speedup vs baseline: 1.0218x; 1.0218x over previous
; __device__ __forceinline__ int otid(int wv) { int t; asm volatile("v_mbcnt_lo_u32_b32 %0, -1, 0\n\tv_mbcnt_hi_u32_b32 %0, -1, %0\n\tv_lshl_add_u32 %0, %1, 6, %0" : "=&v"(t) : "s"(wv)); return t; }
; #define PG8_STAGE(bufoff, gbase, voff) do { _Pragma("unroll") for (int _i = 0; _i < 2; ++_i) \
;         __builtin_amdgcn_global_load_lds((const unsigned*)((const char*)(gbase) + (voff)[_i]), (LAS unsigned*)(lds + (bufoff) + ldsw + _i * 8192), 16, 0, 0); } while (0)
; template <class Epi>
; __device__ __forceinline__ void gemm_phase(int wv, LAS unsigned char* lds, const Gemm g, const StaticOrder& S, const Epi& E) {
;     const int tid = otid(wv), wid = __builtin_amdgcn_readfirstlane(tid >> 6), lane = tid & 63, wr = wid >> 2, wc = wid & 3, fr = lane & 15, fq = lane >> 4;
;     const int K = g.K, nt = K / BK, lda = g.lda;
;     unsigned voffA[2], voffB[2];
; #pragma unroll
;     for (int i = 0; i < 2; ++i) { int R, C; stage_rc(tid * 16 + i * 8192, R, C); const int Rb = Epi::PERM ? ((R & ~31) + perm32(R & 31)) : R;
;         voffA[i] = (unsigned)(R * lda + C) * 2u; voffB[i] = (unsigned)(Rb * K + C) * 2u; }
;     const size_t kstep = (size_t)(BK * 2);
;     const size_t hstepA = (size_t)HALF * lda * 2, hstepB = (size_t)HALF * K * 2;
;     const size_t tstepA = 2 * hstepA, tstepB = 2 * hstepB;
;     const unsigned ldsw = (unsigned)wid * 1024u;
;     const int aoff = lds_byte(wr * 64 + fr, fq * 8), boff = lds_byte(wc * 32 + fr, fq * 8);
;     ...
;     Unit cur, nxt; int ui = 0;
;     if (!S.next(0, cur)) return;
;     f32x4 acc[2][2][4][2];
; #pragma unroll
;     for (int a = 0; a < 2; ++a)
; #pragma unroll
;         for (int b = 0; b < 2; ++b)
; #pragma unroll
;             for (int m = 0; m < 4; ++m)
; #pragma unroll
;                 for (int n = 0; n < 2; ++n) acc[a][b][m][n] = (f32x4){0.f, 0.f, 0.f, 0.f};
;     bf16x8 At[4][2], B0[2][2], B1[2][2];
;     const char* cA = (const char*)g.A + (size_t)cur.pm * tstepA; const char* cB = (const char*)g.Bt + (size_t)cur.pn * tstepB;
;     PG8_STAGE(PG8_SB(0, 0), cB, voffB); PG8_STAGE(PG8_SA(0, 0), cA, voffA); PG8_STAGE(PG8_SB(0, 1), cB + hstepB, voffB); PG8_STAGE(PG8_SA(0, 1), cA + hstepA, voffA);
;     if (wr == 1) PG8_BAR;
;     PG8_WAIT_V(4); PG8_BAR;
;     PG8_STAGE(PG8_SB(1, 0), cB + kstep, voffB); PG8_STAGE(PG8_SA(1, 0), cA + kstep, voffA); PG8_STAGE(PG8_SB(1, 1), cB + hstepB + kstep, voffB);
;     PG8_WAIT_V(6); PG8_BAR;
.LBB0_446:
	v_readlane_b32 s14, v255, 39
	v_readlane_b32 s62, v255, 19
	v_readlane_b32 s12, v255, 32
	v_readlane_b32 s86, v255, 30
	s_mov_b64 s[0:1], 0x2000
	s_andn2_b64 vcc, exec, s[4:5]
	v_readlane_b32 s5, v255, 26
	v_readlane_b32 s6, v255, 41
	v_readlane_b32 s15, v255, 40
	v_readlane_b32 s63, v255, 20
	v_readlane_b32 s4, v255, 29
	v_readlane_b32 s13, v255, 33
	v_readlane_b32 s87, v255, 31
	s_cbranch_vccnz .LBB0_645
	v_readlane_b32 s0, v254, 18
	v_readlane_b32 s1, v254, 19
	v_readlane_b32 s40, v254, 20
	v_mbcnt_lo_u32_b32 v1, -1, 0
	v_mbcnt_hi_u32_b32 v1, -1, v1
	v_lshl_add_u32 v1, s33, 6, v1
	s_andn2_b64 vcc, exec, s[0:1]
	v_readfirstlane_b32 s58, v1
	v_readlane_b32 s41, v254, 21
	v_readlane_b32 s44, v255, 18
	s_cbranch_vccnz .LBB0_507
	v_lshlrev_b32_e32 v5, 4, v1
	v_add_u32_e32 v3, 0x2000, v5
	v_ashrrev_i32_e32 v2, 31, v3
	v_lshrrev_b32_e32 v2, 22, v2
	v_add_u32_e32 v2, v3, v2
	v_ashrrev_i32_e32 v2, 10, v2
	v_mul_i32_i24_e32 v4, 0x400, v2
	v_sub_u32_e32 v3, v3, v4
	v_lshrrev_b32_e32 v4, 4, v3
	v_bitop3_b32 v4, v4, v3, 32 bitop3:0x6c
	v_ashrrev_i32_e32 v3, 31, v4
	v_lshrrev_b32_e32 v3, 26, v3
	v_add_u32_e32 v6, v4, v3
	v_lshlrev_b32_e32 v7, 3, v2
	v_ashrrev_i32_e32 v3, 6, v6
	v_and_b32_e32 v7, -16, v7
	v_add_u32_e32 v7, v3, v7
	v_and_b32_e32 v8, 3, v3
	s_mov_b32 s1, 0x1fffe0
	v_lshrrev_b32_e32 v9, 2, v7
	v_lshlrev_b32_e32 v10, 1, v7
	v_and_b32_e32 v6, 0xc0, v6
	v_and_or_b32 v8, v7, s1, v8
	v_and_b32_e32 v9, 4, v9
	v_and_b32_e32 v10, 24, v10
	v_sub_u32_e32 v4, v4, v6
	v_mov_b32_e32 v12, 1
	v_or3_b32 v8, v8, v9, v10
	v_lshlrev_b32_e32 v9, 5, v2
	v_ashrrev_i16_sdwa v4, v12, sext(v4) dst_sel:DWORD dst_unused:UNUSED_PAD src0_sel:DWORD src1_sel:BYTE_0
	v_and_b32_e32 v9, 32, v9
	v_bfe_i32 v4, v4, 0, 16
	v_add_lshl_u32 v6, v9, v4, 1
	v_lshl_add_u32 v170, v8, 11, v6
	v_and_b32_e32 v13, 15, v7
	v_bfe_u32 v14, v7, 4, 2
	v_and_b32_e32 v15, 0xffffffc0, v7
	v_lshl_or_b32 v13, v13, 2, v14
	v_or_b32_e32 v13, v15, v13
	v_lshl_add_u32 v172, v13, 11, v6
	v_bfe_i32 v6, v1, 27, 1
	v_lshrrev_b32_e32 v6, 22, v6
	v_add_u32_e32 v6, v5, v6
	v_and_b32_e32 v6, 0xfffffc00, v6
	v_sub_u32_e32 v5, v5, v6
	v_lshrrev_b32_e32 v6, 4, v5
	v_bitop3_b32 v7, v6, v5, 32 bitop3:0x6c
	v_ashrrev_i32_e32 v6, 31, v1
	v_lshrrev_b32_e32 v6, 26, v6
	v_ashrrev_i32_e32 v5, 31, v5
	v_add_u32_e32 v6, v1, v6
	v_lshrrev_b32_e32 v5, 26, v5
	v_ashrrev_i32_e32 v6, 6, v6
	v_add_u32_e32 v5, v7, v5
	v_lshlrev_b32_e32 v8, 3, v6
	v_ashrrev_i32_e32 v5, 6, v5
	v_and_b32_e32 v8, -16, v8
	v_add_u32_e32 v8, v5, v8
	v_and_b32_e32 v9, 3, v5
	v_lshrrev_b32_e32 v10, 2, v8
	v_lshlrev_b32_e32 v11, 1, v8
	v_and_or_b32 v9, v8, s1, v9
	v_and_b32_e32 v10, 4, v10
	v_and_b32_e32 v11, 24, v11
	v_or3_b32 v9, v9, v10, v11
	v_mul_i32_i24_e32 v11, 64, v5
	v_sub_u32_e32 v7, v7, v11
	s_ashr_i32 s0, s58, 6
	v_lshlrev_b32_e32 v10, 5, v6
	v_ashrrev_i16_sdwa v7, v12, sext(v7) dst_sel:DWORD dst_unused:UNUSED_PAD src0_sel:DWORD src1_sel:BYTE_0
	s_lshl_b32 s59, s0, 10
	v_and_b32_e32 v10, 32, v10
	v_bfe_i32 v7, v7, 0, 16
	v_add_lshl_u32 v10, v10, v7, 1
	s_add_i32 s60, s59, 0
	v_readlane_b32 s4, v255, 48
	v_lshl_add_u32 v174, v9, 11, v10
	s_add_i32 m0, s60, 0x10000
	v_readlane_b32 s5, v255, 49
	v_and_b32_e32 v13, 15, v8
	v_bfe_u32 v14, v8, 4, 2
	v_and_b32_e32 v15, 0xffffffc0, v8
	v_lshl_or_b32 v13, v13, 2, v14
	v_or_b32_e32 v13, v15, v13
	v_lshl_add_u32 v176, v13, 11, v10
	s_add_i32 s61, s60, 0x2000
	s_add_i32 s64, s60, 0x4000
	s_add_i32 s65, s60, 0x6000
	s_ashr_i32 s66, s58, 8
	global_load_lds_dwordx4 v174, s[4:5]
	s_add_i32 m0, s60, 0x12000
	s_nop 0
	global_load_lds_dwordx4 v170, s[4:5]
	v_readlane_b32 s4, v255, 44
	s_mov_b32 m0, s60
	v_readlane_b32 s5, v255, 45
	s_nop 4
	global_load_lds_dwordx4 v176, s[4:5]
	s_mov_b32 m0, s61
	s_nop 0
	global_load_lds_dwordx4 v172, s[4:5]
	v_readlane_b32 s4, v255, 42
	s_add_i32 m0, s60, 0x14000
	v_readlane_b32 s5, v255, 43
	s_nop 4
	global_load_lds_dwordx4 v174, s[4:5]
	s_add_i32 m0, s60, 0x16000
	s_cmp_lg_u32 s66, 1
	global_load_lds_dwordx4 v170, s[4:5]
	v_readlane_b32 s4, v255, 46
	s_mov_b32 m0, s64
	v_readlane_b32 s5, v255, 47
	s_nop 4
	global_load_lds_dwordx4 v176, s[4:5]
	s_mov_b32 m0, s65
	s_nop 0
	global_load_lds_dwordx4 v172, s[4:5]
	s_cbranch_scc1 .LBB0_450
	s_barrier
.LBB0_450:
	v_readlane_b32 s6, v255, 48
	v_mov_b32_e32 v175, v0
	v_readlane_b32 s7, v255, 49
	v_mov_b32_e32 v171, v0
	v_readlane_b32 s8, v255, 44
	v_lshl_add_u64 v[8:9], s[6:7], 0, v[174:175]
	s_lshl_b32 s0, s0, 5
	v_lshl_add_u64 v[10:11], s[6:7], 0, v[170:171]
	v_mov_b32_e32 v177, v0
	v_readlane_b32 s9, v255, 45
	v_and_b32_e32 v16, 48, v1
	v_lshlrev_b32_e32 v17, 6, v1
	s_movk_i32 s4, 0x3c0
	v_lshlrev_b32_e32 v1, 2, v1
	s_and_b32 s70, s0, 0x60
	s_add_i32 m0, s60, 0x18000
	v_lshl_add_u64 v[8:9], v[8:9], 0, s[38:39]
	v_lshl_add_u64 v[12:13], s[8:9], 0, v[176:177]
	v_mov_b32_e32 v173, v0
	s_lshl_b32 s1, s66, 13
	v_and_or_b32 v16, v17, s4, v16
	v_and_b32_e32 v1, 32, v1
	s_lshl_b32 s0, s70, 7
	s_waitcnt vmcnt(4)
	s_barrier
	global_load_lds_dwordx4 v[8:9], off
	v_lshl_add_u64 v[8:9], v[10:11], 0, s[38:39]
	s_add_i32 m0, s60, 0x1a000
	s_add_i32 s71, s60, 0x8000
	v_lshl_add_u64 v[14:15], s[8:9], 0, v[172:173]
	v_bitop3_b32 v17, v16, s1, v1 bitop3:0xde
	v_bitop3_b32 v1, s0, v16, v1 bitop3:0xf6
	global_load_lds_dwordx4 v[8:9], off
	v_lshl_add_u64 v[8:9], v[12:13], 0, s[38:39]
	s_mov_b32 m0, s71
	s_add_i32 s72, s60, 0xa000
	v_readlane_b32 s0, v255, 50
	global_load_lds_dwordx4 v[8:9], off
	v_lshl_add_u64 v[8:9], v[14:15], 0, s[38:39]
	s_mov_b32 m0, s72
	v_readlane_b32 s1, v255, 51
	global_load_lds_dwordx4 v[8:9], off
	s_add_i32 m0, s60, 0x1c000
	v_lshl_add_u64 v[8:9], s[0:1], 0, v[174:175]
	global_load_lds_dwordx4 v[8:9], off
	v_lshl_add_u64 v[8:9], s[0:1], 0, v[170:171]
	s_add_i32 m0, s60, 0x1e000
	v_readlane_b32 s0, v254, 47
	global_load_lds_dwordx4 v[8:9], off
	v_lshlrev_b32_e32 v8, 14, v6
	v_and_b32_e32 v8, 0xffff8000, v8
	v_lshl_add_u32 v5, v5, 11, v8
	v_and_b32_e32 v6, 1, v6
	v_lshl_or_b32 v5, v6, 6, v5
	v_lshl_add_u32 v180, v7, 1, v5
	v_bfe_u32 v13, v180, 11, 4
	v_bfe_u32 v14, v180, 15, 2
	v_and_b32_e32 v15, 0xfffe07ff, v180
	v_lshl_or_b32 v15, v13, 13, v15
	v_lshl_or_b32 v180, v14, 11, v15
	v_lshlrev_b32_e32 v5, 14, v2
	v_and_b32_e32 v5, 0xffff8000, v5
	s_waitcnt vmcnt(6)
	v_lshl_add_u32 v3, v3, 11, v5
	v_and_b32_e32 v2, 1, v2
	v_lshl_or_b32 v2, v2, 6, v3
	s_lshl_b32 s67, s66, 6
	v_mov_b32_e32 v181, v0
	v_lshl_add_u32 v182, v4, 1, v2
	v_bfe_u32 v13, v182, 11, 4
	v_bfe_u32 v14, v182, 15, 2
	v_and_b32_e32 v15, 0xfffe07ff, v182
	v_lshl_or_b32 v15, v13, 13, v15
	v_lshl_or_b32 v182, v14, 11, v15
	v_mov_b32_e32 v183, v0
	s_mov_b32 s73, 0
	v_add_u32_e32 v179, 0, v17
	v_readlane_b32 s36, v254, 34
	s_mov_b32 s12, s0
	s_mov_b64 s[4:5], s[8:9]
	s_movk_i32 s40, 0x161
	s_movk_i32 s41, 0x5800
	s_barrier
	v_readlane_b32 s1, v254, 48
	s_branch .LBB0_452

; #define PG8_STAGE(bufoff, gbase, voff) do { _Pragma("unroll") for (int _i = 0; _i < 2; ++_i) \
;         __builtin_amdgcn_global_load_lds((const unsigned*)((const char*)(gbase) + (voff)[_i]), (LAS unsigned*)(lds + (bufoff) + ldsw + _i * 8192), 16, 0, 0); } while (0)
; #define PG8_LDA(dst, b, h) do { _Pragma("unroll") for (int m = 0; m < 4; ++m) _Pragma("unroll") for (int k = 0; k < 2; ++k) dst[m][k] = *(const LAS bf16x8*)(lds + PG8_SA(b, h) + aoff + m * 2048 + k * 1024); } while (0)
; #define PG8_LDB(dst, b, h) do { _Pragma("unroll") for (int n = 0; n < 2; ++n) _Pragma("unroll") for (int k = 0; k < 2; ++k) dst[n][k] = *(const LAS bf16x8*)(lds + PG8_SB(b, h) + boff + n * 2048 + k * 1024); } while (0)
; #define PG8_MMA(ai, bj, At, Bt) do { __builtin_amdgcn_s_setprio(1); _Pragma("unroll") for (int m = 0; m < 4; ++m) _Pragma("unroll") for (int n = 0; n < 2; ++n) _Pragma("unroll") for (int k = 0; k < 2; ++k) \
;         acc[ai][bj][m][n] = __builtin_amdgcn_mfma_f32_16x16x32_bf16(Bt[n][k], At[m][k], acc[ai][bj][m][n], 0, 0, 0); __builtin_amdgcn_s_setprio(0); } while (0)
; #define PG8_WAIT_V(n) asm volatile("s_waitcnt vmcnt(" #n ")" ::: "memory")
; #define PG8_WAIT_L(n) asm volatile("s_waitcnt lgkmcnt(" #n ")" ::: "memory")
; #define PG8_BAR __builtin_amdgcn_s_barrier()
; #define PG8_SCHED __builtin_amdgcn_sched_barrier(0)
; template <class Epi>
; __device__ __forceinline__ void gemm_phase(int wv, LAS unsigned char* lds, const Gemm g, const StaticOrder& S, const Epi& E) {
;     ...
;             PG8_LDB(B0, 0, 0); PG8_SCHED; PG8_LDA(At, 0, 0); PG8_STAGE(PG8_SA(1, 1), a1 + hstepA, voffA);
;             PG8_WAIT_L(8); PG8_BAR; PG8_WAIT_L(0); PG8_MMA(0, 0, At, B0); PG8_BAR; PG8_SCHED;
;             PG8_LDB(B1, 0, 1); PG8_STAGE(PG8_SB(0, 0), b2, voffB);
;             PG8_BAR; PG8_WAIT_L(0); PG8_MMA(0, 1, At, B1); PG8_BAR;
;             PG8_LDA(At, 0, 1); PG8_STAGE(PG8_SA(0, 0), a2, voffA);
;             PG8_BAR; PG8_WAIT_L(0); PG8_MMA(1, 0, At, B0); PG8_BAR; PG8_SCHED;
;             PG8_STAGE(PG8_SB(0, 1), b2 + hstepB, voffB);
;             PG8_WAIT_V(6); PG8_BAR; PG8_MMA(1, 1, At, B1); PG8_BAR;
.LBB0_455:
	s_add_u32 s6, s4, 0xfffc0080
	s_addc_u32 s7, s5, -1
	s_add_i32 s42, 0, 0x10000
	v_add_u32_e32 v110, s42, v1
	ds_read_b128 v[98:101], v110
	ds_read_b128 v[102:105], v110 offset:1024
	ds_read_b128 v[106:109], v110 offset:2048
	ds_read_b128 v[110:113], v110 offset:3072
	s_cmp_eq_u32 s17, 12
	s_cselect_b32 s9, s10, s7
	s_cselect_b32 s8, s11, s6
	s_cselect_b32 s7, s13, s16
	s_cselect_b32 s6, s14, s15
	v_lshl_add_u64 v[192:193], s[4:5], 0, v[180:181]
	s_add_i32 m0, s60, 0xc000
	ds_read_b128 v[114:117], v179
	ds_read_b128 v[118:121], v179 offset:1024
	ds_read_b128 v[122:125], v179 offset:2048
	ds_read_b128 v[126:129], v179 offset:3072
	ds_read_b128 v[138:141], v179 offset:4096
	ds_read_b128 v[162:165], v179 offset:5120
	ds_read_b128 v[184:187], v179 offset:6144
	ds_read_b128 v[188:191], v179 offset:7168
	global_load_lds_dwordx4 v[192:193], off
	v_lshl_add_u64 v[192:193], s[4:5], 0, v[182:183]
	s_add_i32 m0, s60, 0xe000
	s_nop 0
	global_load_lds_dwordx4 v[192:193], off
	s_waitcnt lgkmcnt(8)
	s_barrier
	s_waitcnt lgkmcnt(0)
	s_setprio 1
	s_waitcnt lgkmcnt(0)
	v_mfma_f32_16x16x32_bf16 v[146:149], v[98:101], v[114:117], v[146:149]
	v_mfma_f32_16x16x32_bf16 v[46:49], v[106:109], v[114:117], v[46:49]
	v_mfma_f32_16x16x32_bf16 v[134:137], v[98:101], v[122:125], v[134:137]
	v_mfma_f32_16x16x32_bf16 v[38:41], v[106:109], v[122:125], v[38:41]
	v_mfma_f32_16x16x32_bf16 v[130:133], v[98:101], v[138:141], v[130:133]
	v_mfma_f32_16x16x32_bf16 v[34:37], v[106:109], v[138:141], v[34:37]
	v_mfma_f32_16x16x32_bf16 v[142:145], v[98:101], v[184:187], v[142:145]
	v_mfma_f32_16x16x32_bf16 v[42:45], v[106:109], v[184:187], v[42:45]
	v_mfma_f32_16x16x32_bf16 v[146:149], v[102:105], v[118:121], v[146:149]
	v_mfma_f32_16x16x32_bf16 v[46:49], v[110:113], v[118:121], v[46:49]
	v_mfma_f32_16x16x32_bf16 v[134:137], v[102:105], v[126:129], v[134:137]
	v_mfma_f32_16x16x32_bf16 v[38:41], v[110:113], v[126:129], v[38:41]
	v_mfma_f32_16x16x32_bf16 v[130:133], v[102:105], v[162:165], v[130:133]
	v_mfma_f32_16x16x32_bf16 v[34:37], v[110:113], v[162:165], v[34:37]
	v_mfma_f32_16x16x32_bf16 v[142:145], v[102:105], v[188:191], v[142:145]
	v_mfma_f32_16x16x32_bf16 v[42:45], v[110:113], v[188:191], v[42:45]
	s_setprio 0
	s_barrier
	s_add_i32 s44, 0, 0x14000
	s_add_i32 s42, s42, s59
	v_add_u32_e32 v204, s44, v1
	v_lshl_add_u64 v[212:213], s[6:7], 0, v[174:175]
	s_mov_b32 m0, s42
	ds_read_b128 v[192:195], v204
	ds_read_b128 v[196:199], v204 offset:1024
	ds_read_b128 v[200:203], v204 offset:2048
	ds_read_b128 v[204:207], v204 offset:3072
	global_load_lds_dwordx4 v[212:213], off
	v_lshl_add_u64 v[214:215], s[6:7], 0, v[170:171]
	s_add_i32 m0, s42, 0x2000
	s_nop 0
	global_load_lds_dwordx4 v[214:215], off
	s_barrier
	s_waitcnt lgkmcnt(0)
	s_setprio 1
	s_waitcnt lgkmcnt(0)
	v_mfma_f32_16x16x32_bf16 v[166:169], v[192:195], v[114:117], v[166:169]
	v_mfma_f32_16x16x32_bf16 v[62:65], v[200:203], v[114:117], v[62:65]
	v_mfma_f32_16x16x32_bf16 v[54:57], v[200:203], v[122:125], v[54:57]
	v_mfma_f32_16x16x32_bf16 v[50:53], v[200:203], v[138:141], v[50:53]
	v_mfma_f32_16x16x32_bf16 v[58:61], v[200:203], v[184:187], v[58:61]
	v_mfma_f32_16x16x32_bf16 v[166:169], v[196:199], v[118:121], v[166:169]
	v_mfma_f32_16x16x32_bf16 v[62:65], v[204:207], v[118:121], v[62:65]
	v_mfma_f32_16x16x32_bf16 v[114:117], v[192:195], v[122:125], v[154:157]
	v_mfma_f32_16x16x32_bf16 v[54:57], v[204:207], v[126:129], v[54:57]
	v_mfma_f32_16x16x32_bf16 v[118:121], v[192:195], v[138:141], v[150:153]
	v_mfma_f32_16x16x32_bf16 v[50:53], v[204:207], v[162:165], v[50:53]
	v_mfma_f32_16x16x32_bf16 v[122:125], v[192:195], v[184:187], v[158:161]
	v_mfma_f32_16x16x32_bf16 v[58:61], v[204:207], v[188:191], v[58:61]
	v_mfma_f32_16x16x32_bf16 v[114:117], v[196:199], v[126:129], v[114:117]
	v_mfma_f32_16x16x32_bf16 v[118:121], v[196:199], v[162:165], v[118:121]
	v_mfma_f32_16x16x32_bf16 v[122:125], v[196:199], v[188:191], v[122:125]
	s_setprio 0
	s_mov_b32 m0, s60
	v_lshl_add_u64 v[216:217], s[8:9], 0, v[176:177]
	s_barrier
	ds_read_b128 v[126:129], v179 offset:16384
	ds_read_b128 v[138:141], v179 offset:17408
	ds_read_b128 v[150:153], v179 offset:18432
	ds_read_b128 v[154:157], v179 offset:19456
	ds_read_b128 v[158:161], v179 offset:20480
	ds_read_b128 v[162:165], v179 offset:21504
	ds_read_b128 v[184:187], v179 offset:22528
	ds_read_b128 v[188:191], v179 offset:23552
	global_load_lds_dwordx4 v[216:217], off
	v_lshl_add_u64 v[218:219], s[8:9], 0, v[172:173]
	s_mov_b32 m0, s61
	s_nop 0
	global_load_lds_dwordx4 v[218:219], off
	s_barrier
	s_waitcnt lgkmcnt(0)
	s_setprio 1
	s_waitcnt lgkmcnt(0)
	v_mfma_f32_16x16x32_bf16 v[78:81], v[98:101], v[126:129], v[78:81]
	v_mfma_f32_16x16x32_bf16 v[14:17], v[106:109], v[126:129], v[14:17]
	v_mfma_f32_16x16x32_bf16 v[70:73], v[98:101], v[150:153], v[70:73]
	v_mfma_f32_16x16x32_bf16 v[6:9], v[106:109], v[150:153], v[6:9]
	v_mfma_f32_16x16x32_bf16 v[66:69], v[98:101], v[158:161], v[66:69]
	v_mfma_f32_16x16x32_bf16 v[2:5], v[106:109], v[158:161], v[2:5]
	v_mfma_f32_16x16x32_bf16 v[74:77], v[98:101], v[184:187], v[74:77]
	v_mfma_f32_16x16x32_bf16 v[10:13], v[106:109], v[184:187], v[10:13]
	v_mfma_f32_16x16x32_bf16 v[78:81], v[102:105], v[138:141], v[78:81]
	v_mfma_f32_16x16x32_bf16 v[14:17], v[110:113], v[138:141], v[14:17]
	v_mfma_f32_16x16x32_bf16 v[70:73], v[102:105], v[154:157], v[70:73]
	v_mfma_f32_16x16x32_bf16 v[6:9], v[110:113], v[154:157], v[6:9]
	v_mfma_f32_16x16x32_bf16 v[66:69], v[102:105], v[162:165], v[66:69]
	v_mfma_f32_16x16x32_bf16 v[2:5], v[110:113], v[162:165], v[2:5]
	v_mfma_f32_16x16x32_bf16 v[74:77], v[102:105], v[188:191], v[74:77]
	v_mfma_f32_16x16x32_bf16 v[10:13], v[110:113], v[188:191], v[10:13]
	s_setprio 0
	s_barrier
; #define PG8_STAGE(bufoff, gbase, voff) do { _Pragma("unroll") for (int _i = 0; _i < 2; ++_i) \
;         __builtin_amdgcn_global_load_lds((const unsigned*)((const char*)(gbase) + (voff)[_i]), (LAS unsigned*)(lds + (bufoff) + ldsw + _i * 8192), 16, 0, 0); } while (0)
; #define PG8_LDA(dst, b, h) do { _Pragma("unroll") for (int m = 0; m < 4; ++m) _Pragma("unroll") for (int k = 0; k < 2; ++k) dst[m][k] = *(const LAS bf16x8*)(lds + PG8_SA(b, h) + aoff + m * 2048 + k * 1024); } while (0)
; #define PG8_LDB(dst, b, h) do { _Pragma("unroll") for (int n = 0; n < 2; ++n) _Pragma("unroll") for (int k = 0; k < 2; ++k) dst[n][k] = *(const LAS bf16x8*)(lds + PG8_SB(b, h) + boff + n * 2048 + k * 1024); } while (0)
; #define PG8_MMA(ai, bj, At, Bt) do { __builtin_amdgcn_s_setprio(1); _Pragma("unroll") for (int m = 0; m < 4; ++m) _Pragma("unroll") for (int n = 0; n < 2; ++n) _Pragma("unroll") for (int k = 0; k < 2; ++k) \
;         acc[ai][bj][m][n] = __builtin_amdgcn_mfma_f32_16x16x32_bf16(Bt[n][k], At[m][k], acc[ai][bj][m][n], 0, 0, 0); __builtin_amdgcn_s_setprio(0); } while (0)
; #define PG8_WAIT_V(n) asm volatile("s_waitcnt vmcnt(" #n ")" ::: "memory")
; #define PG8_WAIT_L(n) asm volatile("s_waitcnt lgkmcnt(" #n ")" ::: "memory")
; #define PG8_BAR __builtin_amdgcn_s_barrier()
; #define PG8_SCHED __builtin_amdgcn_sched_barrier(0)
; template <class Epi>
; __device__ __forceinline__ void gemm_phase(int wv, LAS unsigned char* lds, const Gemm g, const StaticOrder& S, const Epi& E) {
;     ...
;             PG8_LDA(At, 0, 1); PG8_STAGE(PG8_SA(0, 0), a2, voffA);
;             PG8_BAR; PG8_WAIT_L(0); PG8_MMA(1, 0, At, B0); PG8_BAR; PG8_SCHED;
;             PG8_STAGE(PG8_SB(0, 1), b2 + hstepB, voffB);
;             PG8_WAIT_V(6); PG8_BAR; PG8_MMA(1, 1, At, B1); PG8_BAR;
;             PG8_LDB(B0, 1, 0); PG8_SCHED; PG8_LDA(At, 1, 0); PG8_STAGE(PG8_SA(0, 1), a2 + hstepA, voffA);
;             PG8_WAIT_L(8); PG8_BAR; PG8_WAIT_L(0); PG8_MMA(0, 0, At, B0); PG8_BAR; PG8_SCHED;
;             PG8_LDB(B1, 1, 1); PG8_STAGE(PG8_SB(1, 0), b3, voffB);
;             PG8_BAR; PG8_WAIT_L(0); PG8_MMA(0, 1, At, B1); PG8_BAR;
;             PG8_LDA(At, 1, 1); PG8_STAGE(PG8_SA(1, 0), a3, voffA);
;             PG8_BAR; PG8_WAIT_L(0); PG8_MMA(1, 0, At, B0); PG8_BAR; PG8_SCHED;
	s_add_u32 s54, s6, 0x40000
	s_addc_u32 s55, s7, 0
	s_add_i32 s42, s44, s59
	v_lshl_add_u64 v[98:99], s[54:55], 0, v[174:175]
	s_mov_b32 m0, s42
	s_nop 0
	global_load_lds_dwordx4 v[98:99], off
	v_lshl_add_u64 v[98:99], s[54:55], 0, v[170:171]
	s_add_i32 m0, s42, 0x2000
	s_nop 0
	global_load_lds_dwordx4 v[98:99], off
	s_waitcnt vmcnt(6)
	s_barrier
	s_setprio 1
	v_mfma_f32_16x16x32_bf16 v[94:97], v[192:195], v[126:129], v[94:97]
	v_mfma_f32_16x16x32_bf16 v[30:33], v[200:203], v[126:129], v[30:33]
	v_mfma_f32_16x16x32_bf16 v[86:89], v[192:195], v[150:153], v[86:89]
	v_mfma_f32_16x16x32_bf16 v[26:29], v[200:203], v[150:153], v[26:29]
	v_mfma_f32_16x16x32_bf16 v[82:85], v[192:195], v[158:161], v[82:85]
	v_mfma_f32_16x16x32_bf16 v[18:21], v[200:203], v[158:161], v[18:21]
	v_mfma_f32_16x16x32_bf16 v[90:93], v[192:195], v[184:187], v[90:93]
	v_mfma_f32_16x16x32_bf16 v[22:25], v[200:203], v[184:187], v[22:25]
	v_mfma_f32_16x16x32_bf16 v[94:97], v[196:199], v[138:141], v[94:97]
	v_mfma_f32_16x16x32_bf16 v[30:33], v[204:207], v[138:141], v[30:33]
	v_mfma_f32_16x16x32_bf16 v[86:89], v[196:199], v[154:157], v[86:89]
	v_mfma_f32_16x16x32_bf16 v[26:29], v[204:207], v[154:157], v[26:29]
	v_mfma_f32_16x16x32_bf16 v[82:85], v[196:199], v[162:165], v[82:85]
	v_mfma_f32_16x16x32_bf16 v[18:21], v[204:207], v[162:165], v[18:21]
	v_mfma_f32_16x16x32_bf16 v[90:93], v[196:199], v[188:191], v[90:93]
	v_mfma_f32_16x16x32_bf16 v[22:25], v[204:207], v[188:191], v[22:25]
	s_setprio 0
	s_add_i32 s42, 0, 0x18000
	v_add_u32_e32 v110, s42, v1
	s_barrier
	ds_read_b128 v[98:101], v110
	ds_read_b128 v[102:105], v110 offset:1024
	ds_read_b128 v[106:109], v110 offset:2048
	ds_read_b128 v[110:113], v110 offset:3072
	s_add_u32 s8, s8, 0x40000
	s_addc_u32 s9, s9, 0
	s_mov_b32 m0, s64
	v_lshl_add_u64 v[154:155], s[8:9], 0, v[176:177]
	ds_read_b128 v[126:129], v179 offset:32768
	ds_read_b128 v[138:141], v179 offset:33792
	ds_read_b128 v[150:153], v179 offset:34816
	ds_read_b128 v[158:161], v179 offset:35840
	ds_read_b128 v[162:165], v179 offset:36864
	ds_read_b128 v[184:187], v179 offset:37888
	ds_read_b128 v[188:191], v179 offset:38912
	ds_read_b128 v[192:195], v179 offset:39936
	global_load_lds_dwordx4 v[154:155], off
	v_lshl_add_u64 v[154:155], s[8:9], 0, v[172:173]
	s_mov_b32 m0, s65
	s_nop 0
	global_load_lds_dwordx4 v[154:155], off
	s_waitcnt lgkmcnt(8)
	s_barrier
	s_waitcnt lgkmcnt(0)
	s_setprio 1
	s_waitcnt lgkmcnt(0)
	v_mfma_f32_16x16x32_bf16 v[146:149], v[98:101], v[126:129], v[146:149]
	v_mfma_f32_16x16x32_bf16 v[46:49], v[106:109], v[126:129], v[46:49]
	v_mfma_f32_16x16x32_bf16 v[134:137], v[98:101], v[150:153], v[134:137]
	v_mfma_f32_16x16x32_bf16 v[38:41], v[106:109], v[150:153], v[38:41]
	v_mfma_f32_16x16x32_bf16 v[130:133], v[98:101], v[162:165], v[130:133]
	v_mfma_f32_16x16x32_bf16 v[34:37], v[106:109], v[162:165], v[34:37]
	v_mfma_f32_16x16x32_bf16 v[142:145], v[98:101], v[188:191], v[142:145]
	v_mfma_f32_16x16x32_bf16 v[42:45], v[106:109], v[188:191], v[42:45]
	v_mfma_f32_16x16x32_bf16 v[146:149], v[102:105], v[138:141], v[146:149]
	v_mfma_f32_16x16x32_bf16 v[46:49], v[110:113], v[138:141], v[46:49]
	v_mfma_f32_16x16x32_bf16 v[134:137], v[102:105], v[158:161], v[134:137]
	v_mfma_f32_16x16x32_bf16 v[38:41], v[110:113], v[158:161], v[38:41]
	v_mfma_f32_16x16x32_bf16 v[130:133], v[102:105], v[184:187], v[130:133]
	v_mfma_f32_16x16x32_bf16 v[34:37], v[110:113], v[184:187], v[34:37]
	v_mfma_f32_16x16x32_bf16 v[142:145], v[102:105], v[192:195], v[142:145]
	v_mfma_f32_16x16x32_bf16 v[42:45], v[110:113], v[192:195], v[42:45]
	s_setprio 0
	s_barrier
	s_add_i32 s8, 0, 0x1c000
	v_add_u32_e32 v154, s8, v1
	s_add_i32 s9, s42, s59
	ds_read_b128 v[196:199], v154
	ds_read_b128 v[200:203], v154 offset:1024
	ds_read_b128 v[204:207], v154 offset:2048
	ds_read_b128 v[208:211], v154 offset:3072
	v_lshl_add_u64 v[154:155], v[212:213], 0, s[38:39]
	s_mov_b32 m0, s9
	s_nop 0
	global_load_lds_dwordx4 v[154:155], off
	v_lshl_add_u64 v[154:155], v[214:215], 0, s[38:39]
	s_add_i32 m0, s9, 0x2000
	s_nop 0
	global_load_lds_dwordx4 v[154:155], off
	s_barrier
	s_waitcnt lgkmcnt(0)
	s_setprio 1
	s_waitcnt lgkmcnt(0)
	v_mfma_f32_16x16x32_bf16 v[154:157], v[196:199], v[126:129], v[166:169]
	v_mfma_f32_16x16x32_bf16 v[114:117], v[196:199], v[150:153], v[114:117]
	v_mfma_f32_16x16x32_bf16 v[166:169], v[200:203], v[138:141], v[154:157]
	v_mfma_f32_16x16x32_bf16 v[154:157], v[200:203], v[158:161], v[114:117]
	v_mfma_f32_16x16x32_bf16 v[114:117], v[196:199], v[162:165], v[118:121]
	v_mfma_f32_16x16x32_bf16 v[62:65], v[204:207], v[126:129], v[62:65]
	v_mfma_f32_16x16x32_bf16 v[54:57], v[204:207], v[150:153], v[54:57]
	v_mfma_f32_16x16x32_bf16 v[150:153], v[200:203], v[184:187], v[114:117]
	v_mfma_f32_16x16x32_bf16 v[50:53], v[204:207], v[162:165], v[50:53]
	v_mfma_f32_16x16x32_bf16 v[114:117], v[196:199], v[188:191], v[122:125]
	v_mfma_f32_16x16x32_bf16 v[58:61], v[204:207], v[188:191], v[58:61]
	v_mfma_f32_16x16x32_bf16 v[62:65], v[208:211], v[138:141], v[62:65]
	v_mfma_f32_16x16x32_bf16 v[54:57], v[208:211], v[158:161], v[54:57]
	v_mfma_f32_16x16x32_bf16 v[50:53], v[208:211], v[184:187], v[50:53]
	v_mfma_f32_16x16x32_bf16 v[158:161], v[200:203], v[192:195], v[114:117]
	v_mfma_f32_16x16x32_bf16 v[58:61], v[208:211], v[192:195], v[58:61]
	s_setprio 0
	s_mov_b32 m0, s71
	v_lshl_add_u64 v[192:193], v[216:217], 0, s[38:39]
	s_barrier
	ds_read_b128 v[114:117], v179 offset:49152
	ds_read_b128 v[118:121], v179 offset:50176
	ds_read_b128 v[122:125], v179 offset:51200
	ds_read_b128 v[126:129], v179 offset:52224
	ds_read_b128 v[138:141], v179 offset:53248
	ds_read_b128 v[162:165], v179 offset:54272
	ds_read_b128 v[184:187], v179 offset:55296
	ds_read_b128 v[188:191], v179 offset:56320
	global_load_lds_dwordx4 v[192:193], off
	v_lshl_add_u64 v[192:193], v[218:219], 0, s[38:39]
	s_mov_b32 m0, s72
	s_nop 0
	global_load_lds_dwordx4 v[192:193], off
	s_barrier
; #define PG8_STAGE(bufoff, gbase, voff) do { _Pragma("unroll") for (int _i = 0; _i < 2; ++_i) \
;         __builtin_amdgcn_global_load_lds((const unsigned*)((const char*)(gbase) + (voff)[_i]), (LAS unsigned*)(lds + (bufoff) + ldsw + _i * 8192), 16, 0, 0); } while (0)
; #define PG8_LDA(dst, b, h) do { _Pragma("unroll") for (int m = 0; m < 4; ++m) _Pragma("unroll") for (int k = 0; k < 2; ++k) dst[m][k] = *(const LAS bf16x8*)(lds + PG8_SA(b, h) + aoff + m * 2048 + k * 1024); } while (0)
; #define PG8_WAIT_V(n) asm volatile("s_waitcnt vmcnt(" #n ")" ::: "memory")
; #define PG8_WAIT_L(n) asm volatile("s_waitcnt lgkmcnt(" #n ")" ::: "memory")
; template <class Epi>
; __device__ __forceinline__ void gemm_phase(int wv, LAS unsigned char* lds, const Gemm g, const StaticOrder& S, const Epi& E) {
;     ...
;             PG8_BAR; PG8_WAIT_L(0); PG8_MMA(0, 1, At, B1); PG8_BAR;
;             PG8_LDA(At, 1, 1); PG8_STAGE(PG8_SA(1, 0), a3, voffA);
;             PG8_BAR; PG8_WAIT_L(0); PG8_MMA(1, 0, At, B0); PG8_BAR; PG8_SCHED;
;             PG8_STAGE(PG8_SB(1, 1), b3 + hstepB, voffB);
;             PG8_WAIT_V(6); PG8_BAR; PG8_MMA(1, 1, At, B1); PG8_BAR;
;         }
;     __device__ __forceinline__ void operator()(const f32x4 (&acc)[2][2][4][2], const Unit& u, int wr, int wc, int fr, int fq) const {
;         asm volatile("" : "+v"(fr), "+v"(fq));
;         const int row0 = u.pm * BM + wr * 64 + fr, colt = u.pn * BM + wc * 32 + 8 * fq;
;         const int seq = seq_of_row(u.pm * BM);
;         const float* biasp = bias + (size_t)seq * NUP + colt; const float* cwp = cw + colt;
;         float rs[2][4];
; #pragma unroll
;         for (int ai = 0; ai < 2; ++ai)
; #pragma unroll
;             for (int m = 0; m < 4; ++m) rs[ai][m] = (float)ssin[row0 + ai * HALF + m * 16];
; #pragma unroll
;         for (int ai = 0; ai < 2; ++ai)
; #pragma unroll
;             for (int m = 0; m < 4; ++m) rs[ai][m] = __builtin_amdgcn_rsqf(rs[ai][m] * SSKI + EPSN);
; #pragma unroll
;         for (int n = 0; n < 2; ++n) {
;             f32x4 prm[2][5];
; #pragma unroll
;             for (int bj = 0; bj < 2; ++bj) { const int co = bj * HALF + 4 * n;
;                 prm[bj][0] = *(const f32x4*)(biasp + co); prm[bj][1] = *(const f32x4*)(cwp + co); prm[bj][2] = *(const f32x4*)(cwp + NUP + co); prm[bj][3] = *(const f32x4*)(cwp + 2 * NUP + co); prm[bj][4] = *(const f32x4*)(cwp + 3 * NUP + co); }
	s_waitcnt lgkmcnt(0)
	s_setprio 1
	s_waitcnt lgkmcnt(0)
	v_mfma_f32_16x16x32_bf16 v[78:81], v[98:101], v[114:117], v[78:81]
	v_mfma_f32_16x16x32_bf16 v[14:17], v[106:109], v[114:117], v[14:17]
	v_mfma_f32_16x16x32_bf16 v[70:73], v[98:101], v[122:125], v[70:73]
	v_mfma_f32_16x16x32_bf16 v[6:9], v[106:109], v[122:125], v[6:9]
	v_mfma_f32_16x16x32_bf16 v[66:69], v[98:101], v[138:141], v[66:69]
	v_mfma_f32_16x16x32_bf16 v[2:5], v[106:109], v[138:141], v[2:5]
	v_mfma_f32_16x16x32_bf16 v[74:77], v[98:101], v[184:187], v[74:77]
	v_mfma_f32_16x16x32_bf16 v[10:13], v[106:109], v[184:187], v[10:13]
	v_mfma_f32_16x16x32_bf16 v[78:81], v[102:105], v[118:121], v[78:81]
	v_mfma_f32_16x16x32_bf16 v[14:17], v[110:113], v[118:121], v[14:17]
	v_mfma_f32_16x16x32_bf16 v[70:73], v[102:105], v[126:129], v[70:73]
	v_mfma_f32_16x16x32_bf16 v[6:9], v[110:113], v[126:129], v[6:9]
	v_mfma_f32_16x16x32_bf16 v[66:69], v[102:105], v[162:165], v[66:69]
	v_mfma_f32_16x16x32_bf16 v[2:5], v[110:113], v[162:165], v[2:5]
	v_mfma_f32_16x16x32_bf16 v[74:77], v[102:105], v[188:191], v[74:77]
	v_mfma_f32_16x16x32_bf16 v[10:13], v[110:113], v[188:191], v[10:13]
	s_setprio 0
	s_barrier
	s_add_u32 s6, s6, 0x40080
	s_addc_u32 s7, s7, 0
	s_add_i32 s8, s8, s59
	v_lshl_add_u64 v[98:99], s[6:7], 0, v[174:175]
	s_mov_b32 m0, s8
	s_nop 0
	global_load_lds_dwordx4 v[98:99], off
	v_lshl_add_u64 v[98:99], s[6:7], 0, v[170:171]
	s_add_i32 m0, s8, 0x2000
	s_nop 0
	global_load_lds_dwordx4 v[98:99], off
	s_waitcnt vmcnt(6)
	s_barrier
	s_setprio 1
	v_mfma_f32_16x16x32_bf16 v[94:97], v[196:199], v[114:117], v[94:97]
	v_mfma_f32_16x16x32_bf16 v[30:33], v[204:207], v[114:117], v[30:33]
	v_mfma_f32_16x16x32_bf16 v[86:89], v[196:199], v[122:125], v[86:89]
	v_mfma_f32_16x16x32_bf16 v[26:29], v[204:207], v[122:125], v[26:29]
	v_mfma_f32_16x16x32_bf16 v[82:85], v[196:199], v[138:141], v[82:85]
	v_mfma_f32_16x16x32_bf16 v[18:21], v[204:207], v[138:141], v[18:21]
	v_mfma_f32_16x16x32_bf16 v[90:93], v[196:199], v[184:187], v[90:93]
	v_mfma_f32_16x16x32_bf16 v[22:25], v[204:207], v[184:187], v[22:25]
	v_mfma_f32_16x16x32_bf16 v[94:97], v[200:203], v[118:121], v[94:97]
	v_mfma_f32_16x16x32_bf16 v[30:33], v[208:211], v[118:121], v[30:33]
	v_mfma_f32_16x16x32_bf16 v[86:89], v[200:203], v[126:129], v[86:89]
	v_mfma_f32_16x16x32_bf16 v[26:29], v[208:211], v[126:129], v[26:29]
	v_mfma_f32_16x16x32_bf16 v[82:85], v[200:203], v[162:165], v[82:85]
	v_mfma_f32_16x16x32_bf16 v[18:21], v[208:211], v[162:165], v[18:21]
	v_mfma_f32_16x16x32_bf16 v[90:93], v[200:203], v[188:191], v[90:93]
	v_mfma_f32_16x16x32_bf16 v[22:25], v[208:211], v[188:191], v[22:25]
	s_setprio 0
	s_add_i32 s17, s17, 2
	s_add_u32 s4, s4, 0x100
	s_addc_u32 s5, s5, 0
	s_add_u32 s15, s15, 0x100
	s_addc_u32 s16, s16, 0
	s_cmp_gt_u32 s17, 13
	s_barrier
	s_cbranch_scc0 .LBB0_455
	v_mbcnt_lo_u32_b32 v246, -1, 0
	v_mbcnt_hi_u32_b32 v246, -1, v246
	s_lshl_b32 s4, s12, 8
	s_add_i32 s5, s4, s67
	v_and_b32_e32 v247, 15, v246
	v_bfe_u32 v248, v246, 4, 2
	s_cmpk_lt_u32 s4, 0x4000
	s_movk_i32 s7, 0x2c00
	s_cselect_b32 s7, 0x1600, s7
	s_cmp_gt_i32 s12, 31
	s_cselect_b32 s7, s7, 0
	s_lshl_b32 s7, s7, 2
	s_add_u32 s8, s48, s7
	s_addc_u32 s9, s49, 0
	s_add_u32 s10, s68, 0x5800
	s_addc_u32 s11, s69, 0
	s_add_u32 s14, s68, 0x10800
	s_addc_u32 s15, s69, 0
	v_lshl_add_u32 v249, v247, 2, s5
	v_lshlrev_b32_e32 v249, 3, v249
	s_lshl_b32 s6, s36, 8
	s_or_b32 s6, s6, s70
	v_lshl_add_u32 v244, v248, 3, s6
	v_lshlrev_b32_e32 v244, 2, v244
	global_load_dwordx4 v[184:187], v249, s[22:23]
	global_load_dwordx4 v[188:191], v249, s[22:23] offset:16
	global_load_dwordx4 v[192:195], v249, s[22:23] offset:1024
	global_load_dwordx4 v[196:199], v249, s[22:23] offset:1040
	s_lshl_b32 s42, s12, 2
	s_add_i32 s42, s42, s66
	s_mul_i32 s16, s42, 0x16000
	s_mul_hi_u32 s17, s42, 0x16000
	s_add_u32 s54, s50, s16
	s_addc_u32 s55, s51, s17
	s_mul_i32 s16, s5, 0x1600
	s_mul_hi_u32 s17, s5, 0x1600
	s_add_u32 s74, s90, s16
	s_addc_u32 s75, s91, s17
	s_lshl_b32 s16, s36, 8
	s_lshl_b32 s17, s70, 1
	s_add_i32 s16, s16, s17
	s_add_u32 s74, s74, s16
	s_addc_u32 s75, s75, 0
	s_add_u32 s12, s68, 0xb000
	s_addc_u32 s13, s69, 0
	global_load_dwordx4 v[98:101], v244, s[8:9]
	global_load_dwordx4 v[102:105], v244, s[68:69]
	global_load_dwordx4 v[106:109], v244, s[10:11]
	global_load_dwordx4 v[110:113], v244, s[12:13]
	global_load_dwordx4 v[114:117], v244, s[14:15]
	global_load_dwordx4 v[118:121], v244, s[8:9] offset:512
	global_load_dwordx4 v[122:125], v244, s[68:69] offset:512
	global_load_dwordx4 v[126:129], v244, s[10:11] offset:512
	global_load_dwordx4 v[138:141], v244, s[12:13] offset:512
	global_load_dwordx4 v[162:165], v244, s[14:15] offset:512
	v_cmp_eq_u32_e64 s[4:5], 0, v247
	v_cmp_eq_u32_e64 s[6:7], 15, v247
	v_mul_u32_u24_e32 v245, 0x5800, v247
	v_lshl_add_u32 v245, v248, 4, v245
	v_mov_b32_e32 v240, 0xbfb8aa3b
	v_mov_b32_e32 v241, 0xbfb8aa3b
	s_waitcnt vmcnt(0)
;     __device__ __forceinline__ void operator()(const f32x4 (&acc)[2][2][4][2], const Unit& u, int wr, int wc, int fr, int fq) const {
;     ...
; #pragma unroll
;         for (int ai = 0; ai < 2; ++ai)
; #pragma unroll
;             for (int m = 0; m < 4; ++m) rs[ai][m] = (float)ssin[row0 + ai * HALF + m * 16];
; #pragma unroll
;         for (int ai = 0; ai < 2; ++ai)
; #pragma unroll
;             for (int m = 0; m < 4; ++m) rs[ai][m] = __builtin_amdgcn_rsqf(rs[ai][m] * SSKI + EPSN);
; #pragma unroll
;         for (int n = 0; n < 2; ++n) {
;             f32x4 prm[2][5];
; #pragma unroll
;             for (int bj = 0; bj < 2; ++bj) { const int co = bj * HALF + 4 * n;
;                 prm[bj][0] = *(const f32x4*)(biasp + co); prm[bj][1] = *(const f32x4*)(cwp + co); prm[bj][2] = *(const f32x4*)(cwp + NUP + co); prm[bj][3] = *(const f32x4*)(cwp + 2 * NUP + co); prm[bj][4] = *(const f32x4*)(cwp + 3 * NUP + co); }
; #pragma unroll
;             for (int ai = 0; ai < 2; ++ai) {
;                 float* ep = edge + (size_t)(u.pm * 4 + ai * 2 + wr) * 4 * NUP + colt;
;                 f32x4 SG[4];
; #pragma unroll
;                 for (int bjr = 0; bjr < 2; ++bjr) { const int bj = 1 - bjr; const int co = bj * HALF + 4 * n;
;                     f32x4 U[4];
; #pragma unroll
;                     for (int m = 0; m < 4; ++m) U[m] = acc[ai][bj][m][n] * rs[ai][m] + prm[bj][0];
;                     if (fr < 2) *(f32x4*)(ep + (size_t)fr * NUP + co) = U[0];
;                     if (fr >= 14) *(f32x4*)(ep + (size_t)(fr - 12) * NUP + co) = U[3];
; #pragma unroll
;                     for (int m = 0; m < 4; ++m) { const f32x4 sp = (fr == 15 && m > 0) ? U[m > 0 ? m - 1 : 0] : U[m]; const f32x4 sn = (fr == 0 && m < 3) ? U[m < 3 ? m + 1 : 3] : U[m];
;                         f32x4 pv, nv;
; #pragma unroll
;                         for (int j = 0; j < 4; ++j) { pv[j] = __int_as_float(__builtin_amdgcn_update_dpp(0, __float_as_int(sp[j]), 0x121, 0xf, 0xf, false)); nv[j] = __int_as_float(__builtin_amdgcn_update_dpp(0, __float_as_int(sn[j]), 0x12F, 0xf, 0xf, false)); }
;                         const f32x4 R = prm[bj][1] * pv + prm[bj][2] * U[m] + prm[bj][3] * nv + prm[bj][4];
;                         if (bj == 1) {
; #pragma unroll
;                             for (int j = 0; j < 4; ++j) SG[m][j] = R[j] * __builtin_amdgcn_rcpf(1.0f + __expf(-R[j])); }
	v_cvt_f32_u32_e32 v242, v185
	v_cvt_f32_u32_e32 v243, v184
	v_fmamk_f32 v242, v242, 0x4f800000, v243
	v_fmamk_f32 v242, v242, 0x30800000, v251
	v_rsq_f32_e32 v224, v242
	v_cvt_f32_u32_e32 v242, v187
	v_cvt_f32_u32_e32 v243, v186
	v_fmamk_f32 v242, v242, 0x4f800000, v243
	v_fmamk_f32 v242, v242, 0x30800000, v251
	v_rsq_f32_e32 v225, v242
	v_cvt_f32_u32_e32 v242, v189
	v_cvt_f32_u32_e32 v243, v188
	v_fmamk_f32 v242, v242, 0x4f800000, v243
	v_fmamk_f32 v242, v242, 0x30800000, v251
	v_rsq_f32_e32 v226, v242
	v_cvt_f32_u32_e32 v242, v191
	v_cvt_f32_u32_e32 v243, v190
	v_fmamk_f32 v242, v242, 0x4f800000, v243
	v_fmamk_f32 v242, v242, 0x30800000, v251
	v_rsq_f32_e32 v227, v242
	v_cvt_f32_u32_e32 v242, v193
	v_cvt_f32_u32_e32 v243, v192
	v_fmamk_f32 v242, v242, 0x4f800000, v243
	v_fmamk_f32 v242, v242, 0x30800000, v251
	v_rsq_f32_e32 v228, v242
	v_cvt_f32_u32_e32 v242, v195
	v_cvt_f32_u32_e32 v243, v194
	v_fmamk_f32 v242, v242, 0x4f800000, v243
	v_fmamk_f32 v242, v242, 0x30800000, v251
	v_rsq_f32_e32 v229, v242
	v_cvt_f32_u32_e32 v242, v197
	v_cvt_f32_u32_e32 v243, v196
	v_fmamk_f32 v242, v242, 0x4f800000, v243
	v_fmamk_f32 v242, v242, 0x30800000, v251
	v_rsq_f32_e32 v230, v242
	v_cvt_f32_u32_e32 v242, v199
	v_cvt_f32_u32_e32 v243, v198
	v_fmamk_f32 v242, v242, 0x4f800000, v243
	v_fmamk_f32 v242, v242, 0x30800000, v251
	v_rsq_f32_e32 v231, v242
	global_load_dwordx4 v[184:187], v244, s[8:9] offset:16
	global_load_dwordx4 v[188:191], v244, s[68:69] offset:16
	global_load_dwordx4 v[192:195], v244, s[10:11] offset:16
	global_load_dwordx4 v[196:199], v244, s[12:13] offset:16
	global_load_dwordx4 v[200:203], v244, s[14:15] offset:16
	global_load_dwordx4 v[204:207], v244, s[8:9] offset:528
	global_load_dwordx4 v[208:211], v244, s[68:69] offset:528
	global_load_dwordx4 v[212:215], v244, s[10:11] offset:528
	global_load_dwordx4 v[216:219], v244, s[12:13] offset:528
	global_load_dwordx4 v[220:223], v244, s[14:15] offset:528
	v_pk_fma_f32 v[166:167], v[166:167], v[224:225], v[118:119] op_sel_hi:[1,0,1]
	v_pk_fma_f32 v[168:169], v[168:169], v[224:225], v[120:121] op_sel_hi:[1,0,1]
	v_pk_fma_f32 v[154:155], v[154:155], v[224:225], v[118:119] op_sel:[0,1,0] op_sel_hi:[1,1,1]
	v_pk_fma_f32 v[156:157], v[156:157], v[224:225], v[120:121] op_sel:[0,1,0] op_sel_hi:[1,1,1]
	v_pk_fma_f32 v[150:151], v[150:151], v[226:227], v[118:119] op_sel_hi:[1,0,1]
	v_pk_fma_f32 v[152:153], v[152:153], v[226:227], v[120:121] op_sel_hi:[1,0,1]
	v_pk_fma_f32 v[158:159], v[158:159], v[226:227], v[118:119] op_sel:[0,1,0] op_sel_hi:[1,1,1]
	v_pk_fma_f32 v[160:161], v[160:161], v[226:227], v[120:121] op_sel:[0,1,0] op_sel_hi:[1,1,1]
	s_mov_b64 exec, s[4:5]
	global_store_dwordx4 v244, v[166:169], s[54:55] offset:512
	s_add_u32 s16, s54, 0x5800
	s_addc_u32 s17, s55, 0
	global_store_dwordx4 v244, v[154:157], s[16:17] offset:512
	s_mov_b64 exec, s[6:7]
	s_add_u32 s56, s54, 0xb000
	s_addc_u32 s57, s55, 0
	global_store_dwordx4 v244, v[150:153], s[56:57] offset:512
	s_add_u32 s16, s54, 0x10800
	s_addc_u32 s17, s55, 0
	global_store_dwordx4 v244, v[158:161], s[16:17] offset:512
	s_mov_b64 exec, -1
	v_pk_fma_f32 v[232:233], v[126:127], v[166:167], v[162:163]
	v_pk_fma_f32 v[234:235], v[126:127], v[154:155], v[162:163]
	v_pk_fma_f32 v[236:237], v[126:127], v[150:151], v[162:163]
	v_pk_fma_f32 v[238:239], v[126:127], v[158:159], v[162:163]
	v_pk_fma_f32 v[234:235], v[122:123], v[166:167], v[234:235]
	v_pk_fma_f32 v[236:237], v[122:123], v[154:155], v[236:237]
	v_pk_fma_f32 v[238:239], v[122:123], v[150:151], v[238:239]
	v_pk_fma_f32 v[232:233], v[138:139], v[154:155], v[232:233]
	v_pk_fma_f32 v[234:235], v[138:139], v[150:151], v[234:235]
	v_pk_fma_f32 v[236:237], v[138:139], v[158:159], v[236:237]
	v_fmac_f32_dpp v232, v158, v122 row_ror:1 row_mask:0xf bank_mask:0xf
	v_fmac_f32_dpp v233, v159, v123 row_ror:1 row_mask:0xf bank_mask:0xf
	v_fmac_f32_dpp v238, v166, v138 row_ror:15 row_mask:0xf bank_mask:0xf
	v_fmac_f32_dpp v239, v167, v139 row_ror:15 row_mask:0xf bank_mask:0xf
	v_pk_mul_f32 v[166:167], v[232:233], v[240:241]
	v_pk_mul_f32 v[154:155], v[234:235], v[240:241]
	v_pk_mul_f32 v[150:151], v[236:237], v[240:241]
	v_pk_mul_f32 v[158:159], v[238:239], v[240:241]
	v_exp_f32_e32 v166, v166
	v_exp_f32_e32 v167, v167
	v_exp_f32_e32 v154, v154
	v_exp_f32_e32 v155, v155
	v_exp_f32_e32 v150, v150
	v_exp_f32_e32 v151, v151
	v_exp_f32_e32 v158, v158
	v_exp_f32_e32 v159, v159
	v_add_f32_e32 v166, 1.0, v166
	v_add_f32_e32 v167, 1.0, v167
	v_add_f32_e32 v154, 1.0, v154
	v_add_f32_e32 v155, 1.0, v155
	v_add_f32_e32 v150, 1.0, v150
	v_add_f32_e32 v151, 1.0, v151
	v_add_f32_e32 v158, 1.0, v158
	v_add_f32_e32 v159, 1.0, v159
	v_rcp_f32_e32 v166, v166
	v_rcp_f32_e32 v167, v167
	v_rcp_f32_e32 v154, v154
	v_rcp_f32_e32 v155, v155
	v_rcp_f32_e32 v150, v150
	v_rcp_f32_e32 v151, v151
	v_rcp_f32_e32 v158, v158
	v_rcp_f32_e32 v159, v159
	v_pk_mul_f32 v[166:167], v[232:233], v[166:167]
	v_pk_mul_f32 v[154:155], v[234:235], v[154:155]
	v_pk_mul_f32 v[150:151], v[236:237], v[150:151]
	v_pk_mul_f32 v[158:159], v[238:239], v[158:159]
	v_pk_fma_f32 v[232:233], v[128:129], v[168:169], v[164:165]
	v_pk_fma_f32 v[234:235], v[128:129], v[156:157], v[164:165]
	v_pk_fma_f32 v[236:237], v[128:129], v[152:153], v[164:165]
	v_pk_fma_f32 v[238:239], v[128:129], v[160:161], v[164:165]
	v_pk_fma_f32 v[234:235], v[124:125], v[168:169], v[234:235]
	v_pk_fma_f32 v[236:237], v[124:125], v[156:157], v[236:237]
	v_pk_fma_f32 v[238:239], v[124:125], v[152:153], v[238:239]
	v_pk_fma_f32 v[232:233], v[140:141], v[156:157], v[232:233]
	v_pk_fma_f32 v[234:235], v[140:141], v[152:153], v[234:235]
	v_pk_fma_f32 v[236:237], v[140:141], v[160:161], v[236:237]
; __device__ __forceinline__ unsigned cvt_pk_bf16_asm(float lo, float hi) { unsigned r; asm volatile("v_cvt_pk_bf16_f32 %0, %1, %2" : "=v"(r) : "v"(lo), "v"(hi)); return r; }
;     __device__ __forceinline__ void operator()(const f32x4 (&acc)[2][2][4][2], const Unit& u, int wr, int wc, int fr, int fq) const {
;     ...
;             for (int ai = 0; ai < 2; ++ai) {
;                 float* ep = edge + (size_t)(u.pm * 4 + ai * 2 + wr) * 4 * NUP + colt;
;                 f32x4 SG[4];
; #pragma unroll
;                 for (int bjr = 0; bjr < 2; ++bjr) { const int bj = 1 - bjr; const int co = bj * HALF + 4 * n;
;                     f32x4 U[4];
; #pragma unroll
;                     for (int m = 0; m < 4; ++m) U[m] = acc[ai][bj][m][n] * rs[ai][m] + prm[bj][0];
;                     if (fr < 2) *(f32x4*)(ep + (size_t)fr * NUP + co) = U[0];
;                     if (fr >= 14) *(f32x4*)(ep + (size_t)(fr - 12) * NUP + co) = U[3];
; #pragma unroll
;                     for (int m = 0; m < 4; ++m) { const f32x4 sp = (fr == 15 && m > 0) ? U[m > 0 ? m - 1 : 0] : U[m]; const f32x4 sn = (fr == 0 && m < 3) ? U[m < 3 ? m + 1 : 3] : U[m];
;                         f32x4 pv, nv;
; #pragma unroll
;                         for (int j = 0; j < 4; ++j) { pv[j] = __int_as_float(__builtin_amdgcn_update_dpp(0, __float_as_int(sp[j]), 0x121, 0xf, 0xf, false)); nv[j] = __int_as_float(__builtin_amdgcn_update_dpp(0, __float_as_int(sn[j]), 0x12F, 0xf, 0xf, false)); }
;                         const f32x4 R = prm[bj][1] * pv + prm[bj][2] * U[m] + prm[bj][3] * nv + prm[bj][4];
;                         if (bj == 1) {
; #pragma unroll
;                             for (int j = 0; j < 4; ++j) SG[m][j] = R[j] * __builtin_amdgcn_rcpf(1.0f + __expf(-R[j])); }
;                         else { const int r = row0 + ai * HALF + m * 16; const bool skip = (m == 0 && fr == 0) || (m == 3 && fr == 15);
;                             const f32x4 o = R * SG[m]; u32x2 w; w.x = cvt_pk_bf16_asm(o[0], o[1]); w.y = cvt_pk_bf16_asm(o[2], o[3]);
;                             if (!skip) *(u32x2*)(act + (size_t)r * FFD + u.pn * 128 + wc * 32 + 8 * fq + 4 * n) = w; } } } }
	v_fmac_f32_dpp v232, v160, v124 row_ror:1 row_mask:0xf bank_mask:0xf
	v_fmac_f32_dpp v233, v161, v125 row_ror:1 row_mask:0xf bank_mask:0xf
	v_fmac_f32_dpp v238, v168, v140 row_ror:15 row_mask:0xf bank_mask:0xf
	v_fmac_f32_dpp v239, v169, v141 row_ror:15 row_mask:0xf bank_mask:0xf
	v_pk_mul_f32 v[168:169], v[232:233], v[240:241]
	v_pk_mul_f32 v[156:157], v[234:235], v[240:241]
	v_pk_mul_f32 v[152:153], v[236:237], v[240:241]
	v_pk_mul_f32 v[160:161], v[238:239], v[240:241]
	v_exp_f32_e32 v168, v168
	v_exp_f32_e32 v169, v169
	v_exp_f32_e32 v156, v156
	v_exp_f32_e32 v157, v157
	v_exp_f32_e32 v152, v152
	v_exp_f32_e32 v153, v153
	v_exp_f32_e32 v160, v160
	v_exp_f32_e32 v161, v161
	v_add_f32_e32 v168, 1.0, v168
	v_add_f32_e32 v169, 1.0, v169
	v_add_f32_e32 v156, 1.0, v156
	v_add_f32_e32 v157, 1.0, v157
	v_add_f32_e32 v152, 1.0, v152
	v_add_f32_e32 v153, 1.0, v153
	v_add_f32_e32 v160, 1.0, v160
	v_add_f32_e32 v161, 1.0, v161
	v_rcp_f32_e32 v168, v168
	v_rcp_f32_e32 v169, v169
	v_rcp_f32_e32 v156, v156
	v_rcp_f32_e32 v157, v157
	v_rcp_f32_e32 v152, v152
	v_rcp_f32_e32 v153, v153
	v_rcp_f32_e32 v160, v160
	v_rcp_f32_e32 v161, v161
	v_pk_mul_f32 v[168:169], v[232:233], v[168:169]
	v_pk_mul_f32 v[156:157], v[234:235], v[156:157]
	v_pk_mul_f32 v[152:153], v[236:237], v[152:153]
	v_pk_mul_f32 v[160:161], v[238:239], v[160:161]
	v_pk_fma_f32 v[146:147], v[146:147], v[224:225], v[98:99] op_sel_hi:[1,0,1]
	v_pk_fma_f32 v[148:149], v[148:149], v[224:225], v[100:101] op_sel_hi:[1,0,1]
	v_pk_fma_f32 v[134:135], v[134:135], v[224:225], v[98:99] op_sel:[0,1,0] op_sel_hi:[1,1,1]
	v_pk_fma_f32 v[136:137], v[136:137], v[224:225], v[100:101] op_sel:[0,1,0] op_sel_hi:[1,1,1]
	v_pk_fma_f32 v[130:131], v[130:131], v[226:227], v[98:99] op_sel_hi:[1,0,1]
	v_pk_fma_f32 v[132:133], v[132:133], v[226:227], v[100:101] op_sel_hi:[1,0,1]
	v_pk_fma_f32 v[142:143], v[142:143], v[226:227], v[98:99] op_sel:[0,1,0] op_sel_hi:[1,1,1]
	v_pk_fma_f32 v[144:145], v[144:145], v[226:227], v[100:101] op_sel:[0,1,0] op_sel_hi:[1,1,1]
	s_mov_b64 exec, s[4:5]
	global_store_dwordx4 v244, v[146:149], s[54:55]
	s_add_u32 s16, s54, 0x5800
	s_addc_u32 s17, s55, 0
	global_store_dwordx4 v244, v[134:137], s[16:17]
	s_mov_b64 exec, s[6:7]
	s_add_u32 s56, s54, 0xb000
	s_addc_u32 s57, s55, 0
	global_store_dwordx4 v244, v[130:133], s[56:57]
	s_add_u32 s16, s54, 0x10800
	s_addc_u32 s17, s55, 0
	global_store_dwordx4 v244, v[142:145], s[16:17]
	s_mov_b64 exec, -1
	v_pk_fma_f32 v[232:233], v[106:107], v[146:147], v[114:115]
	v_pk_fma_f32 v[234:235], v[106:107], v[134:135], v[114:115]
	v_pk_fma_f32 v[236:237], v[106:107], v[130:131], v[114:115]
	v_pk_fma_f32 v[238:239], v[106:107], v[142:143], v[114:115]
	v_pk_fma_f32 v[234:235], v[102:103], v[146:147], v[234:235]
	v_pk_fma_f32 v[236:237], v[102:103], v[134:135], v[236:237]
	v_pk_fma_f32 v[238:239], v[102:103], v[130:131], v[238:239]
	v_pk_fma_f32 v[232:233], v[110:111], v[134:135], v[232:233]
	v_pk_fma_f32 v[234:235], v[110:111], v[130:131], v[234:235]
	v_pk_fma_f32 v[236:237], v[110:111], v[142:143], v[236:237]
	v_fmac_f32_dpp v232, v142, v102 row_ror:1 row_mask:0xf bank_mask:0xf
	v_fmac_f32_dpp v233, v143, v103 row_ror:1 row_mask:0xf bank_mask:0xf
	v_fmac_f32_dpp v238, v146, v110 row_ror:15 row_mask:0xf bank_mask:0xf
	v_fmac_f32_dpp v239, v147, v111 row_ror:15 row_mask:0xf bank_mask:0xf
	v_pk_mul_f32 v[232:233], v[232:233], v[166:167]
	v_pk_mul_f32 v[234:235], v[234:235], v[154:155]
	v_pk_mul_f32 v[236:237], v[236:237], v[150:151]
	v_pk_mul_f32 v[238:239], v[238:239], v[158:159]
	v_cvt_pk_bf16_f32 v146, v232, v233
	v_cvt_pk_bf16_f32 v134, v234, v235
	v_cvt_pk_bf16_f32 v130, v236, v237
	v_cvt_pk_bf16_f32 v142, v238, v239
	v_pk_fma_f32 v[232:233], v[108:109], v[148:149], v[116:117]
	v_pk_fma_f32 v[234:235], v[108:109], v[136:137], v[116:117]
	v_pk_fma_f32 v[236:237], v[108:109], v[132:133], v[116:117]
	v_pk_fma_f32 v[238:239], v[108:109], v[144:145], v[116:117]
	v_pk_fma_f32 v[234:235], v[104:105], v[148:149], v[234:235]
	v_pk_fma_f32 v[236:237], v[104:105], v[136:137], v[236:237]
	v_pk_fma_f32 v[238:239], v[104:105], v[132:133], v[238:239]
	v_pk_fma_f32 v[232:233], v[112:113], v[136:137], v[232:233]
	v_pk_fma_f32 v[234:235], v[112:113], v[132:133], v[234:235]
	v_pk_fma_f32 v[236:237], v[112:113], v[144:145], v[236:237]
	v_fmac_f32_dpp v232, v144, v104 row_ror:1 row_mask:0xf bank_mask:0xf
	v_fmac_f32_dpp v233, v145, v105 row_ror:1 row_mask:0xf bank_mask:0xf
	v_fmac_f32_dpp v238, v148, v112 row_ror:15 row_mask:0xf bank_mask:0xf
	v_fmac_f32_dpp v239, v149, v113 row_ror:15 row_mask:0xf bank_mask:0xf
	v_pk_mul_f32 v[232:233], v[232:233], v[168:169]
	v_pk_mul_f32 v[234:235], v[234:235], v[156:157]
	v_pk_mul_f32 v[236:237], v[236:237], v[152:153]
	v_pk_mul_f32 v[238:239], v[238:239], v[160:161]
	v_cvt_pk_bf16_f32 v147, v232, v233
	v_cvt_pk_bf16_f32 v135, v234, v235
	v_cvt_pk_bf16_f32 v131, v236, v237
	v_cvt_pk_bf16_f32 v143, v238, v239
	s_add_u32 s54, s54, 0x2c000
	s_addc_u32 s55, s55, 0
	v_pk_fma_f32 v[94:95], v[94:95], v[228:229], v[118:119] op_sel_hi:[1,0,1]
	v_pk_fma_f32 v[96:97], v[96:97], v[228:229], v[120:121] op_sel_hi:[1,0,1]
	v_pk_fma_f32 v[86:87], v[86:87], v[228:229], v[118:119] op_sel:[0,1,0] op_sel_hi:[1,1,1]
	v_pk_fma_f32 v[88:89], v[88:89], v[228:229], v[120:121] op_sel:[0,1,0] op_sel_hi:[1,1,1]
	v_pk_fma_f32 v[82:83], v[82:83], v[230:231], v[118:119] op_sel_hi:[1,0,1]
	v_pk_fma_f32 v[84:85], v[84:85], v[230:231], v[120:121] op_sel_hi:[1,0,1]
	v_pk_fma_f32 v[90:91], v[90:91], v[230:231], v[118:119] op_sel:[0,1,0] op_sel_hi:[1,1,1]
	v_pk_fma_f32 v[92:93], v[92:93], v[230:231], v[120:121] op_sel:[0,1,0] op_sel_hi:[1,1,1]
	s_mov_b64 exec, s[4:5]
; __device__ __forceinline__ unsigned cvt_pk_bf16_asm(float lo, float hi) { unsigned r; asm volatile("v_cvt_pk_bf16_f32 %0, %1, %2" : "=v"(r) : "v"(lo), "v"(hi)); return r; }
;     __device__ __forceinline__ void operator()(const f32x4 (&acc)[2][2][4][2], const Unit& u, int wr, int wc, int fr, int fq) const {
;     ...
;             for (int ai = 0; ai < 2; ++ai) {
;                 float* ep = edge + (size_t)(u.pm * 4 + ai * 2 + wr) * 4 * NUP + colt;
;                 f32x4 SG[4];
; #pragma unroll
;                 for (int bjr = 0; bjr < 2; ++bjr) { const int bj = 1 - bjr; const int co = bj * HALF + 4 * n;
;                     f32x4 U[4];
; #pragma unroll
;                     for (int m = 0; m < 4; ++m) U[m] = acc[ai][bj][m][n] * rs[ai][m] + prm[bj][0];
;                     if (fr < 2) *(f32x4*)(ep + (size_t)fr * NUP + co) = U[0];
;                     if (fr >= 14) *(f32x4*)(ep + (size_t)(fr - 12) * NUP + co) = U[3];
; #pragma unroll
;                     for (int m = 0; m < 4; ++m) { const f32x4 sp = (fr == 15 && m > 0) ? U[m > 0 ? m - 1 : 0] : U[m]; const f32x4 sn = (fr == 0 && m < 3) ? U[m < 3 ? m + 1 : 3] : U[m];
;                         f32x4 pv, nv;
; #pragma unroll
;                         for (int j = 0; j < 4; ++j) { pv[j] = __int_as_float(__builtin_amdgcn_update_dpp(0, __float_as_int(sp[j]), 0x121, 0xf, 0xf, false)); nv[j] = __int_as_float(__builtin_amdgcn_update_dpp(0, __float_as_int(sn[j]), 0x12F, 0xf, 0xf, false)); }
;                         const f32x4 R = prm[bj][1] * pv + prm[bj][2] * U[m] + prm[bj][3] * nv + prm[bj][4];
;                         if (bj == 1) {
; #pragma unroll
;                             for (int j = 0; j < 4; ++j) SG[m][j] = R[j] * __builtin_amdgcn_rcpf(1.0f + __expf(-R[j])); }
;                         else { const int r = row0 + ai * HALF + m * 16; const bool skip = (m == 0 && fr == 0) || (m == 3 && fr == 15);
;                             const f32x4 o = R * SG[m]; u32x2 w; w.x = cvt_pk_bf16_asm(o[0], o[1]); w.y = cvt_pk_bf16_asm(o[2], o[3]);
;                             if (!skip) *(u32x2*)(act + (size_t)r * FFD + u.pn * 128 + wc * 32 + 8 * fq + 4 * n) = w; } } } }
	global_store_dwordx4 v244, v[94:97], s[54:55] offset:512
	s_add_u32 s16, s54, 0x5800
	s_addc_u32 s17, s55, 0
	global_store_dwordx4 v244, v[86:89], s[16:17] offset:512
	s_mov_b64 exec, s[6:7]
	s_add_u32 s56, s54, 0xb000
	s_addc_u32 s57, s55, 0
	global_store_dwordx4 v244, v[82:85], s[56:57] offset:512
	s_add_u32 s16, s54, 0x10800
	s_addc_u32 s17, s55, 0
	global_store_dwordx4 v244, v[90:93], s[16:17] offset:512
	s_mov_b64 exec, -1
	v_pk_fma_f32 v[232:233], v[126:127], v[94:95], v[162:163]
	v_pk_fma_f32 v[234:235], v[126:127], v[86:87], v[162:163]
	v_pk_fma_f32 v[236:237], v[126:127], v[82:83], v[162:163]
	v_pk_fma_f32 v[238:239], v[126:127], v[90:91], v[162:163]
	v_pk_fma_f32 v[234:235], v[122:123], v[94:95], v[234:235]
	v_pk_fma_f32 v[236:237], v[122:123], v[86:87], v[236:237]
	v_pk_fma_f32 v[238:239], v[122:123], v[82:83], v[238:239]
	v_pk_fma_f32 v[232:233], v[138:139], v[86:87], v[232:233]
	v_pk_fma_f32 v[234:235], v[138:139], v[82:83], v[234:235]
	v_pk_fma_f32 v[236:237], v[138:139], v[90:91], v[236:237]
	v_fmac_f32_dpp v232, v90, v122 row_ror:1 row_mask:0xf bank_mask:0xf
	v_fmac_f32_dpp v233, v91, v123 row_ror:1 row_mask:0xf bank_mask:0xf
	v_fmac_f32_dpp v238, v94, v138 row_ror:15 row_mask:0xf bank_mask:0xf
	v_fmac_f32_dpp v239, v95, v139 row_ror:15 row_mask:0xf bank_mask:0xf
	v_pk_mul_f32 v[94:95], v[232:233], v[240:241]
	v_pk_mul_f32 v[86:87], v[234:235], v[240:241]
	v_pk_mul_f32 v[82:83], v[236:237], v[240:241]
	v_pk_mul_f32 v[90:91], v[238:239], v[240:241]
	v_exp_f32_e32 v94, v94
	v_exp_f32_e32 v95, v95
	v_exp_f32_e32 v86, v86
	v_exp_f32_e32 v87, v87
	v_exp_f32_e32 v82, v82
	v_exp_f32_e32 v83, v83
	v_exp_f32_e32 v90, v90
	v_exp_f32_e32 v91, v91
	v_add_f32_e32 v94, 1.0, v94
	v_add_f32_e32 v95, 1.0, v95
	v_add_f32_e32 v86, 1.0, v86
	v_add_f32_e32 v87, 1.0, v87
	v_add_f32_e32 v82, 1.0, v82
	v_add_f32_e32 v83, 1.0, v83
	v_add_f32_e32 v90, 1.0, v90
	v_add_f32_e32 v91, 1.0, v91
	v_rcp_f32_e32 v94, v94
	v_rcp_f32_e32 v95, v95
	v_rcp_f32_e32 v86, v86
	v_rcp_f32_e32 v87, v87
	v_rcp_f32_e32 v82, v82
	v_rcp_f32_e32 v83, v83
	v_rcp_f32_e32 v90, v90
	v_rcp_f32_e32 v91, v91
	v_pk_mul_f32 v[94:95], v[232:233], v[94:95]
	v_pk_mul_f32 v[86:87], v[234:235], v[86:87]
	v_pk_mul_f32 v[82:83], v[236:237], v[82:83]
	v_pk_mul_f32 v[90:91], v[238:239], v[90:91]
	v_pk_fma_f32 v[232:233], v[128:129], v[96:97], v[164:165]
	v_pk_fma_f32 v[234:235], v[128:129], v[88:89], v[164:165]
	v_pk_fma_f32 v[236:237], v[128:129], v[84:85], v[164:165]
	v_pk_fma_f32 v[238:239], v[128:129], v[92:93], v[164:165]
	v_pk_fma_f32 v[234:235], v[124:125], v[96:97], v[234:235]
	v_pk_fma_f32 v[236:237], v[124:125], v[88:89], v[236:237]
	v_pk_fma_f32 v[238:239], v[124:125], v[84:85], v[238:239]
	v_pk_fma_f32 v[232:233], v[140:141], v[88:89], v[232:233]
	v_pk_fma_f32 v[234:235], v[140:141], v[84:85], v[234:235]
	v_pk_fma_f32 v[236:237], v[140:141], v[92:93], v[236:237]
	v_fmac_f32_dpp v232, v92, v124 row_ror:1 row_mask:0xf bank_mask:0xf
	v_fmac_f32_dpp v233, v93, v125 row_ror:1 row_mask:0xf bank_mask:0xf
	v_fmac_f32_dpp v238, v96, v140 row_ror:15 row_mask:0xf bank_mask:0xf
	v_fmac_f32_dpp v239, v97, v141 row_ror:15 row_mask:0xf bank_mask:0xf
	v_pk_mul_f32 v[96:97], v[232:233], v[240:241]
	v_pk_mul_f32 v[88:89], v[234:235], v[240:241]
	v_pk_mul_f32 v[84:85], v[236:237], v[240:241]
	v_pk_mul_f32 v[92:93], v[238:239], v[240:241]
	v_exp_f32_e32 v96, v96
	v_exp_f32_e32 v97, v97
	v_exp_f32_e32 v88, v88
	v_exp_f32_e32 v89, v89
	v_exp_f32_e32 v84, v84
	v_exp_f32_e32 v85, v85
	v_exp_f32_e32 v92, v92
	v_exp_f32_e32 v93, v93
	v_add_f32_e32 v96, 1.0, v96
	v_add_f32_e32 v97, 1.0, v97
	v_add_f32_e32 v88, 1.0, v88
	v_add_f32_e32 v89, 1.0, v89
	v_add_f32_e32 v84, 1.0, v84
	v_add_f32_e32 v85, 1.0, v85
	v_add_f32_e32 v92, 1.0, v92
	v_add_f32_e32 v93, 1.0, v93
	v_rcp_f32_e32 v96, v96
	v_rcp_f32_e32 v97, v97
	v_rcp_f32_e32 v88, v88
	v_rcp_f32_e32 v89, v89
	v_rcp_f32_e32 v84, v84
	v_rcp_f32_e32 v85, v85
	v_rcp_f32_e32 v92, v92
	v_rcp_f32_e32 v93, v93
	v_pk_mul_f32 v[96:97], v[232:233], v[96:97]
	v_pk_mul_f32 v[88:89], v[234:235], v[88:89]
	v_pk_mul_f32 v[84:85], v[236:237], v[84:85]
	v_pk_mul_f32 v[92:93], v[238:239], v[92:93]
	v_pk_fma_f32 v[78:79], v[78:79], v[228:229], v[98:99] op_sel_hi:[1,0,1]
	v_pk_fma_f32 v[80:81], v[80:81], v[228:229], v[100:101] op_sel_hi:[1,0,1]
	v_pk_fma_f32 v[70:71], v[70:71], v[228:229], v[98:99] op_sel:[0,1,0] op_sel_hi:[1,1,1]
	v_pk_fma_f32 v[72:73], v[72:73], v[228:229], v[100:101] op_sel:[0,1,0] op_sel_hi:[1,1,1]
	v_pk_fma_f32 v[66:67], v[66:67], v[230:231], v[98:99] op_sel_hi:[1,0,1]
	v_pk_fma_f32 v[68:69], v[68:69], v[230:231], v[100:101] op_sel_hi:[1,0,1]
	v_pk_fma_f32 v[74:75], v[74:75], v[230:231], v[98:99] op_sel:[0,1,0] op_sel_hi:[1,1,1]
	v_pk_fma_f32 v[76:77], v[76:77], v[230:231], v[100:101] op_sel:[0,1,0] op_sel_hi:[1,1,1]
	s_mov_b64 exec, s[4:5]
	global_store_dwordx4 v244, v[78:81], s[54:55]
	s_add_u32 s16, s54, 0x5800
	s_addc_u32 s17, s55, 0
	global_store_dwordx4 v244, v[70:73], s[16:17]
	s_mov_b64 exec, s[6:7]
	s_add_u32 s56, s54, 0xb000
	s_addc_u32 s57, s55, 0
	global_store_dwordx4 v244, v[66:69], s[56:57]
	s_add_u32 s16, s54, 0x10800
	s_addc_u32 s17, s55, 0
	global_store_dwordx4 v244, v[74:77], s[16:17]
	s_mov_b64 exec, -1
	v_pk_fma_f32 v[232:233], v[106:107], v[78:79], v[114:115]
	v_pk_fma_f32 v[234:235], v[106:107], v[70:71], v[114:115]
	v_pk_fma_f32 v[236:237], v[106:107], v[66:67], v[114:115]
	v_pk_fma_f32 v[238:239], v[106:107], v[74:75], v[114:115]
	v_pk_fma_f32 v[234:235], v[102:103], v[78:79], v[234:235]
	v_pk_fma_f32 v[236:237], v[102:103], v[70:71], v[236:237]
	v_pk_fma_f32 v[238:239], v[102:103], v[66:67], v[238:239]
;     __device__ __forceinline__ void operator()(const f32x4 (&acc)[2][2][4][2], const Unit& u, int wr, int wc, int fr, int fq) const {
;     ...
;             for (int bj = 0; bj < 2; ++bj) { const int co = bj * HALF + 4 * n;
;                 prm[bj][0] = *(const f32x4*)(biasp + co); prm[bj][1] = *(const f32x4*)(cwp + co); prm[bj][2] = *(const f32x4*)(cwp + NUP + co); prm[bj][3] = *(const f32x4*)(cwp + 2 * NUP + co); prm[bj][4] = *(const f32x4*)(cwp + 3 * NUP + co); }
; #pragma unroll
;             for (int ai = 0; ai < 2; ++ai) {
;                 float* ep = edge + (size_t)(u.pm * 4 + ai * 2 + wr) * 4 * NUP + colt;
;                 f32x4 SG[4];
; #pragma unroll
;                 for (int bjr = 0; bjr < 2; ++bjr) { const int bj = 1 - bjr; const int co = bj * HALF + 4 * n;
;                     f32x4 U[4];
; #pragma unroll
;                     for (int m = 0; m < 4; ++m) U[m] = acc[ai][bj][m][n] * rs[ai][m] + prm[bj][0];
;                     if (fr < 2) *(f32x4*)(ep + (size_t)fr * NUP + co) = U[0];
;                     if (fr >= 14) *(f32x4*)(ep + (size_t)(fr - 12) * NUP + co) = U[3];
; #pragma unroll
;                     for (int m = 0; m < 4; ++m) { const f32x4 sp = (fr == 15 && m > 0) ? U[m > 0 ? m - 1 : 0] : U[m]; const f32x4 sn = (fr == 0 && m < 3) ? U[m < 3 ? m + 1 : 3] : U[m];
;                         f32x4 pv, nv;
; #pragma unroll
;                         for (int j = 0; j < 4; ++j) { pv[j] = __int_as_float(__builtin_amdgcn_update_dpp(0, __float_as_int(sp[j]), 0x121, 0xf, 0xf, false)); nv[j] = __int_as_float(__builtin_amdgcn_update_dpp(0, __float_as_int(sn[j]), 0x12F, 0xf, 0xf, false)); }
;                         const f32x4 R = prm[bj][1] * pv + prm[bj][2] * U[m] + prm[bj][3] * nv + prm[bj][4];
;                         if (bj == 1) {
; #pragma unroll
;                             for (int j = 0; j < 4; ++j) SG[m][j] = R[j] * __builtin_amdgcn_rcpf(1.0f + __expf(-R[j])); }
;                         else { const int r = row0 + ai * HALF + m * 16; const bool skip = (m == 0 && fr == 0) || (m == 3 && fr == 15);
;                             const f32x4 o = R * SG[m]; u32x2 w; w.x = cvt_pk_bf16_asm(o[0], o[1]); w.y = cvt_pk_bf16_asm(o[2], o[3]);
;                             if (!skip) *(u32x2*)(act + (size_t)r * FFD + u.pn * 128 + wc * 32 + 8 * fq + 4 * n) = w; } } } }
	v_pk_fma_f32 v[232:233], v[110:111], v[70:71], v[232:233]
	v_pk_fma_f32 v[234:235], v[110:111], v[66:67], v[234:235]
	v_pk_fma_f32 v[236:237], v[110:111], v[74:75], v[236:237]
	v_fmac_f32_dpp v232, v74, v102 row_ror:1 row_mask:0xf bank_mask:0xf
	v_fmac_f32_dpp v233, v75, v103 row_ror:1 row_mask:0xf bank_mask:0xf
	v_fmac_f32_dpp v238, v78, v110 row_ror:15 row_mask:0xf bank_mask:0xf
	v_fmac_f32_dpp v239, v79, v111 row_ror:15 row_mask:0xf bank_mask:0xf
	v_pk_mul_f32 v[232:233], v[232:233], v[94:95]
	v_pk_mul_f32 v[234:235], v[234:235], v[86:87]
	v_pk_mul_f32 v[236:237], v[236:237], v[82:83]
	v_pk_mul_f32 v[238:239], v[238:239], v[90:91]
	v_cvt_pk_bf16_f32 v78, v232, v233
	v_cvt_pk_bf16_f32 v70, v234, v235
	v_cvt_pk_bf16_f32 v66, v236, v237
	v_cvt_pk_bf16_f32 v74, v238, v239
	v_pk_fma_f32 v[232:233], v[108:109], v[80:81], v[116:117]
	v_pk_fma_f32 v[234:235], v[108:109], v[72:73], v[116:117]
	v_pk_fma_f32 v[236:237], v[108:109], v[68:69], v[116:117]
	v_pk_fma_f32 v[238:239], v[108:109], v[76:77], v[116:117]
	v_pk_fma_f32 v[234:235], v[104:105], v[80:81], v[234:235]
	v_pk_fma_f32 v[236:237], v[104:105], v[72:73], v[236:237]
	v_pk_fma_f32 v[238:239], v[104:105], v[68:69], v[238:239]
	v_pk_fma_f32 v[232:233], v[112:113], v[72:73], v[232:233]
	v_pk_fma_f32 v[234:235], v[112:113], v[68:69], v[234:235]
	v_pk_fma_f32 v[236:237], v[112:113], v[76:77], v[236:237]
	v_fmac_f32_dpp v232, v76, v104 row_ror:1 row_mask:0xf bank_mask:0xf
	v_fmac_f32_dpp v233, v77, v105 row_ror:1 row_mask:0xf bank_mask:0xf
	v_fmac_f32_dpp v238, v80, v112 row_ror:15 row_mask:0xf bank_mask:0xf
	v_fmac_f32_dpp v239, v81, v113 row_ror:15 row_mask:0xf bank_mask:0xf
	v_pk_mul_f32 v[232:233], v[232:233], v[96:97]
	v_pk_mul_f32 v[234:235], v[234:235], v[88:89]
	v_pk_mul_f32 v[236:237], v[236:237], v[84:85]
	v_pk_mul_f32 v[238:239], v[238:239], v[92:93]
	v_cvt_pk_bf16_f32 v79, v232, v233
	v_cvt_pk_bf16_f32 v71, v234, v235
	v_cvt_pk_bf16_f32 v67, v236, v237
	v_cvt_pk_bf16_f32 v75, v238, v239
	s_waitcnt vmcnt(16)
	s_sub_u32 s54, s54, 0x2c000
	s_subb_u32 s55, s55, 0
	v_pk_fma_f32 v[62:63], v[62:63], v[224:225], v[204:205] op_sel_hi:[1,0,1]
	v_pk_fma_f32 v[64:65], v[64:65], v[224:225], v[206:207] op_sel_hi:[1,0,1]
	v_pk_fma_f32 v[54:55], v[54:55], v[224:225], v[204:205] op_sel:[0,1,0] op_sel_hi:[1,1,1]
	v_pk_fma_f32 v[56:57], v[56:57], v[224:225], v[206:207] op_sel:[0,1,0] op_sel_hi:[1,1,1]
	v_pk_fma_f32 v[50:51], v[50:51], v[226:227], v[204:205] op_sel_hi:[1,0,1]
	v_pk_fma_f32 v[52:53], v[52:53], v[226:227], v[206:207] op_sel_hi:[1,0,1]
	v_pk_fma_f32 v[58:59], v[58:59], v[226:227], v[204:205] op_sel:[0,1,0] op_sel_hi:[1,1,1]
	v_pk_fma_f32 v[60:61], v[60:61], v[226:227], v[206:207] op_sel:[0,1,0] op_sel_hi:[1,1,1]
	s_mov_b64 exec, s[4:5]
	global_store_dwordx4 v244, v[62:65], s[54:55] offset:528
	s_add_u32 s16, s54, 0x5800
	s_addc_u32 s17, s55, 0
	global_store_dwordx4 v244, v[54:57], s[16:17] offset:528
	s_mov_b64 exec, s[6:7]
	s_add_u32 s56, s54, 0xb000
	s_addc_u32 s57, s55, 0
	global_store_dwordx4 v244, v[50:53], s[56:57] offset:528
	s_add_u32 s16, s54, 0x10800
	s_addc_u32 s17, s55, 0
	global_store_dwordx4 v244, v[58:61], s[16:17] offset:528
	s_mov_b64 exec, -1
	v_pk_fma_f32 v[232:233], v[212:213], v[62:63], v[220:221]
	v_pk_fma_f32 v[234:235], v[212:213], v[54:55], v[220:221]
	v_pk_fma_f32 v[236:237], v[212:213], v[50:51], v[220:221]
	v_pk_fma_f32 v[238:239], v[212:213], v[58:59], v[220:221]
	v_pk_fma_f32 v[234:235], v[208:209], v[62:63], v[234:235]
	v_pk_fma_f32 v[236:237], v[208:209], v[54:55], v[236:237]
	v_pk_fma_f32 v[238:239], v[208:209], v[50:51], v[238:239]
	v_pk_fma_f32 v[232:233], v[216:217], v[54:55], v[232:233]
	v_pk_fma_f32 v[234:235], v[216:217], v[50:51], v[234:235]
	v_pk_fma_f32 v[236:237], v[216:217], v[58:59], v[236:237]
	v_fmac_f32_dpp v232, v58, v208 row_ror:1 row_mask:0xf bank_mask:0xf
	v_fmac_f32_dpp v233, v59, v209 row_ror:1 row_mask:0xf bank_mask:0xf
	v_fmac_f32_dpp v238, v62, v216 row_ror:15 row_mask:0xf bank_mask:0xf
	v_fmac_f32_dpp v239, v63, v217 row_ror:15 row_mask:0xf bank_mask:0xf
	v_pk_mul_f32 v[62:63], v[232:233], v[240:241]
	v_pk_mul_f32 v[54:55], v[234:235], v[240:241]
	v_pk_mul_f32 v[50:51], v[236:237], v[240:241]
	v_pk_mul_f32 v[58:59], v[238:239], v[240:241]
	v_exp_f32_e32 v62, v62
	v_exp_f32_e32 v63, v63
	v_exp_f32_e32 v54, v54
	v_exp_f32_e32 v55, v55
	v_exp_f32_e32 v50, v50
	v_exp_f32_e32 v51, v51
	v_exp_f32_e32 v58, v58
	v_exp_f32_e32 v59, v59
	v_add_f32_e32 v62, 1.0, v62
	v_add_f32_e32 v63, 1.0, v63
	v_add_f32_e32 v54, 1.0, v54
	v_add_f32_e32 v55, 1.0, v55
	v_add_f32_e32 v50, 1.0, v50
	v_add_f32_e32 v51, 1.0, v51
	v_add_f32_e32 v58, 1.0, v58
	v_add_f32_e32 v59, 1.0, v59
	v_rcp_f32_e32 v62, v62
	v_rcp_f32_e32 v63, v63
	v_rcp_f32_e32 v54, v54
	v_rcp_f32_e32 v55, v55
	v_rcp_f32_e32 v50, v50
	v_rcp_f32_e32 v51, v51
	v_rcp_f32_e32 v58, v58
	v_rcp_f32_e32 v59, v59
	v_pk_mul_f32 v[62:63], v[232:233], v[62:63]
	v_pk_mul_f32 v[54:55], v[234:235], v[54:55]
	v_pk_mul_f32 v[50:51], v[236:237], v[50:51]
	v_pk_mul_f32 v[58:59], v[238:239], v[58:59]
	v_pk_fma_f32 v[232:233], v[214:215], v[64:65], v[222:223]
	v_pk_fma_f32 v[234:235], v[214:215], v[56:57], v[222:223]
	v_pk_fma_f32 v[236:237], v[214:215], v[52:53], v[222:223]
	v_pk_fma_f32 v[238:239], v[214:215], v[60:61], v[222:223]
	v_pk_fma_f32 v[234:235], v[210:211], v[64:65], v[234:235]
	v_pk_fma_f32 v[236:237], v[210:211], v[56:57], v[236:237]
	v_pk_fma_f32 v[238:239], v[210:211], v[52:53], v[238:239]
	v_pk_fma_f32 v[232:233], v[218:219], v[56:57], v[232:233]
	v_pk_fma_f32 v[234:235], v[218:219], v[52:53], v[234:235]
	v_pk_fma_f32 v[236:237], v[218:219], v[60:61], v[236:237]
; __device__ __forceinline__ unsigned cvt_pk_bf16_asm(float lo, float hi) { unsigned r; asm volatile("v_cvt_pk_bf16_f32 %0, %1, %2" : "=v"(r) : "v"(lo), "v"(hi)); return r; }
;     __device__ __forceinline__ void operator()(const f32x4 (&acc)[2][2][4][2], const Unit& u, int wr, int wc, int fr, int fq) const {
;     ...
;             for (int ai = 0; ai < 2; ++ai) {
;                 float* ep = edge + (size_t)(u.pm * 4 + ai * 2 + wr) * 4 * NUP + colt;
;                 f32x4 SG[4];
; #pragma unroll
;                 for (int bjr = 0; bjr < 2; ++bjr) { const int bj = 1 - bjr; const int co = bj * HALF + 4 * n;
;                     f32x4 U[4];
; #pragma unroll
;                     for (int m = 0; m < 4; ++m) U[m] = acc[ai][bj][m][n] * rs[ai][m] + prm[bj][0];
;                     if (fr < 2) *(f32x4*)(ep + (size_t)fr * NUP + co) = U[0];
;                     if (fr >= 14) *(f32x4*)(ep + (size_t)(fr - 12) * NUP + co) = U[3];
; #pragma unroll
;                     for (int m = 0; m < 4; ++m) { const f32x4 sp = (fr == 15 && m > 0) ? U[m > 0 ? m - 1 : 0] : U[m]; const f32x4 sn = (fr == 0 && m < 3) ? U[m < 3 ? m + 1 : 3] : U[m];
;                         f32x4 pv, nv;
; #pragma unroll
;                         for (int j = 0; j < 4; ++j) { pv[j] = __int_as_float(__builtin_amdgcn_update_dpp(0, __float_as_int(sp[j]), 0x121, 0xf, 0xf, false)); nv[j] = __int_as_float(__builtin_amdgcn_update_dpp(0, __float_as_int(sn[j]), 0x12F, 0xf, 0xf, false)); }
;                         const f32x4 R = prm[bj][1] * pv + prm[bj][2] * U[m] + prm[bj][3] * nv + prm[bj][4];
;                         if (bj == 1) {
; #pragma unroll
;                             for (int j = 0; j < 4; ++j) SG[m][j] = R[j] * __builtin_amdgcn_rcpf(1.0f + __expf(-R[j])); }
;                         else { const int r = row0 + ai * HALF + m * 16; const bool skip = (m == 0 && fr == 0) || (m == 3 && fr == 15);
;                             const f32x4 o = R * SG[m]; u32x2 w; w.x = cvt_pk_bf16_asm(o[0], o[1]); w.y = cvt_pk_bf16_asm(o[2], o[3]);
;                             if (!skip) *(u32x2*)(act + (size_t)r * FFD + u.pn * 128 + wc * 32 + 8 * fq + 4 * n) = w; } } } }
	v_fmac_f32_dpp v232, v60, v210 row_ror:1 row_mask:0xf bank_mask:0xf
	v_fmac_f32_dpp v233, v61, v211 row_ror:1 row_mask:0xf bank_mask:0xf
	v_fmac_f32_dpp v238, v64, v218 row_ror:15 row_mask:0xf bank_mask:0xf
	v_fmac_f32_dpp v239, v65, v219 row_ror:15 row_mask:0xf bank_mask:0xf
	v_pk_mul_f32 v[64:65], v[232:233], v[240:241]
	v_pk_mul_f32 v[56:57], v[234:235], v[240:241]
	v_pk_mul_f32 v[52:53], v[236:237], v[240:241]
	v_pk_mul_f32 v[60:61], v[238:239], v[240:241]
	v_exp_f32_e32 v64, v64
	v_exp_f32_e32 v65, v65
	v_exp_f32_e32 v56, v56
	v_exp_f32_e32 v57, v57
	v_exp_f32_e32 v52, v52
	v_exp_f32_e32 v53, v53
	v_exp_f32_e32 v60, v60
	v_exp_f32_e32 v61, v61
	v_add_f32_e32 v64, 1.0, v64
	v_add_f32_e32 v65, 1.0, v65
	v_add_f32_e32 v56, 1.0, v56
	v_add_f32_e32 v57, 1.0, v57
	v_add_f32_e32 v52, 1.0, v52
	v_add_f32_e32 v53, 1.0, v53
	v_add_f32_e32 v60, 1.0, v60
	v_add_f32_e32 v61, 1.0, v61
	v_rcp_f32_e32 v64, v64
	v_rcp_f32_e32 v65, v65
	v_rcp_f32_e32 v56, v56
	v_rcp_f32_e32 v57, v57
	v_rcp_f32_e32 v52, v52
	v_rcp_f32_e32 v53, v53
	v_rcp_f32_e32 v60, v60
	v_rcp_f32_e32 v61, v61
	v_pk_mul_f32 v[64:65], v[232:233], v[64:65]
	v_pk_mul_f32 v[56:57], v[234:235], v[56:57]
	v_pk_mul_f32 v[52:53], v[236:237], v[52:53]
	v_pk_mul_f32 v[60:61], v[238:239], v[60:61]
	v_pk_fma_f32 v[46:47], v[46:47], v[224:225], v[184:185] op_sel_hi:[1,0,1]
	v_pk_fma_f32 v[48:49], v[48:49], v[224:225], v[186:187] op_sel_hi:[1,0,1]
	v_pk_fma_f32 v[38:39], v[38:39], v[224:225], v[184:185] op_sel:[0,1,0] op_sel_hi:[1,1,1]
	v_pk_fma_f32 v[40:41], v[40:41], v[224:225], v[186:187] op_sel:[0,1,0] op_sel_hi:[1,1,1]
	v_pk_fma_f32 v[34:35], v[34:35], v[226:227], v[184:185] op_sel_hi:[1,0,1]
	v_pk_fma_f32 v[36:37], v[36:37], v[226:227], v[186:187] op_sel_hi:[1,0,1]
	v_pk_fma_f32 v[42:43], v[42:43], v[226:227], v[184:185] op_sel:[0,1,0] op_sel_hi:[1,1,1]
	v_pk_fma_f32 v[44:45], v[44:45], v[226:227], v[186:187] op_sel:[0,1,0] op_sel_hi:[1,1,1]
	s_mov_b64 exec, s[4:5]
	global_store_dwordx4 v244, v[46:49], s[54:55] offset:16
	s_add_u32 s16, s54, 0x5800
	s_addc_u32 s17, s55, 0
	global_store_dwordx4 v244, v[38:41], s[16:17] offset:16
	s_mov_b64 exec, s[6:7]
	s_add_u32 s56, s54, 0xb000
	s_addc_u32 s57, s55, 0
	global_store_dwordx4 v244, v[34:37], s[56:57] offset:16
	s_add_u32 s16, s54, 0x10800
	s_addc_u32 s17, s55, 0
	global_store_dwordx4 v244, v[42:45], s[16:17] offset:16
	s_mov_b64 exec, -1
	v_pk_fma_f32 v[232:233], v[192:193], v[46:47], v[200:201]
	v_pk_fma_f32 v[234:235], v[192:193], v[38:39], v[200:201]
	v_pk_fma_f32 v[236:237], v[192:193], v[34:35], v[200:201]
	v_pk_fma_f32 v[238:239], v[192:193], v[42:43], v[200:201]
	v_pk_fma_f32 v[234:235], v[188:189], v[46:47], v[234:235]
	v_pk_fma_f32 v[236:237], v[188:189], v[38:39], v[236:237]
	v_pk_fma_f32 v[238:239], v[188:189], v[34:35], v[238:239]
	v_pk_fma_f32 v[232:233], v[196:197], v[38:39], v[232:233]
	v_pk_fma_f32 v[234:235], v[196:197], v[34:35], v[234:235]
	v_pk_fma_f32 v[236:237], v[196:197], v[42:43], v[236:237]
	v_fmac_f32_dpp v232, v42, v188 row_ror:1 row_mask:0xf bank_mask:0xf
	v_fmac_f32_dpp v233, v43, v189 row_ror:1 row_mask:0xf bank_mask:0xf
	v_fmac_f32_dpp v238, v46, v196 row_ror:15 row_mask:0xf bank_mask:0xf
	v_fmac_f32_dpp v239, v47, v197 row_ror:15 row_mask:0xf bank_mask:0xf
	v_pk_mul_f32 v[232:233], v[232:233], v[62:63]
	v_pk_mul_f32 v[234:235], v[234:235], v[54:55]
	v_pk_mul_f32 v[236:237], v[236:237], v[50:51]
	v_pk_mul_f32 v[238:239], v[238:239], v[58:59]
	v_cvt_pk_bf16_f32 v148, v232, v233
	v_cvt_pk_bf16_f32 v136, v234, v235
	v_cvt_pk_bf16_f32 v132, v236, v237
	v_cvt_pk_bf16_f32 v144, v238, v239
	v_pk_fma_f32 v[232:233], v[194:195], v[48:49], v[202:203]
	v_pk_fma_f32 v[234:235], v[194:195], v[40:41], v[202:203]
	v_pk_fma_f32 v[236:237], v[194:195], v[36:37], v[202:203]
	v_pk_fma_f32 v[238:239], v[194:195], v[44:45], v[202:203]
	v_pk_fma_f32 v[234:235], v[190:191], v[48:49], v[234:235]
	v_pk_fma_f32 v[236:237], v[190:191], v[40:41], v[236:237]
	v_pk_fma_f32 v[238:239], v[190:191], v[36:37], v[238:239]
	v_pk_fma_f32 v[232:233], v[198:199], v[40:41], v[232:233]
	v_pk_fma_f32 v[234:235], v[198:199], v[36:37], v[234:235]
	v_pk_fma_f32 v[236:237], v[198:199], v[44:45], v[236:237]
	v_fmac_f32_dpp v232, v44, v190 row_ror:1 row_mask:0xf bank_mask:0xf
	v_fmac_f32_dpp v233, v45, v191 row_ror:1 row_mask:0xf bank_mask:0xf
	v_fmac_f32_dpp v238, v48, v198 row_ror:15 row_mask:0xf bank_mask:0xf
	v_fmac_f32_dpp v239, v49, v199 row_ror:15 row_mask:0xf bank_mask:0xf
	v_pk_mul_f32 v[232:233], v[232:233], v[64:65]
	v_pk_mul_f32 v[234:235], v[234:235], v[56:57]
	v_pk_mul_f32 v[236:237], v[236:237], v[52:53]
	v_pk_mul_f32 v[238:239], v[238:239], v[60:61]
	v_cvt_pk_bf16_f32 v149, v232, v233
	v_cvt_pk_bf16_f32 v137, v234, v235
	v_cvt_pk_bf16_f32 v133, v236, v237
	v_cvt_pk_bf16_f32 v145, v238, v239
	s_add_u32 s16, s74, 0x0
	s_addc_u32 s17, s75, 0
	s_not_b64 exec, s[4:5]
	global_store_dwordx4 v245, v[146:149], s[16:17]
	s_mov_b64 exec, -1
	s_add_u32 s16, s74, 0x1600
	s_addc_u32 s17, s75, 0
	global_store_dwordx4 v245, v[134:137], s[16:17]
	s_add_u32 s16, s74, 0x2c00
	s_addc_u32 s17, s75, 0
	global_store_dwordx4 v245, v[130:133], s[16:17]
	s_add_u32 s16, s74, 0x4200
	s_addc_u32 s17, s75, 0
	s_not_b64 exec, s[6:7]
	global_store_dwordx4 v245, v[142:145], s[16:17]
	s_mov_b64 exec, -1
	s_add_u32 s54, s54, 0x2c000
	s_addc_u32 s55, s55, 0
	v_pk_fma_f32 v[30:31], v[30:31], v[228:229], v[204:205] op_sel_hi:[1,0,1]
	v_pk_fma_f32 v[32:33], v[32:33], v[228:229], v[206:207] op_sel_hi:[1,0,1]
	v_pk_fma_f32 v[26:27], v[26:27], v[228:229], v[204:205] op_sel:[0,1,0] op_sel_hi:[1,1,1]
	v_pk_fma_f32 v[28:29], v[28:29], v[228:229], v[206:207] op_sel:[0,1,0] op_sel_hi:[1,1,1]
; __device__ __forceinline__ unsigned cvt_pk_bf16_asm(float lo, float hi) { unsigned r; asm volatile("v_cvt_pk_bf16_f32 %0, %1, %2" : "=v"(r) : "v"(lo), "v"(hi)); return r; }
;     __device__ __forceinline__ void operator()(const f32x4 (&acc)[2][2][4][2], const Unit& u, int wr, int wc, int fr, int fq) const {
;     ...
;             for (int ai = 0; ai < 2; ++ai) {
;                 float* ep = edge + (size_t)(u.pm * 4 + ai * 2 + wr) * 4 * NUP + colt;
;                 f32x4 SG[4];
; #pragma unroll
;                 for (int bjr = 0; bjr < 2; ++bjr) { const int bj = 1 - bjr; const int co = bj * HALF + 4 * n;
;                     f32x4 U[4];
; #pragma unroll
;                     for (int m = 0; m < 4; ++m) U[m] = acc[ai][bj][m][n] * rs[ai][m] + prm[bj][0];
;                     if (fr < 2) *(f32x4*)(ep + (size_t)fr * NUP + co) = U[0];
;                     if (fr >= 14) *(f32x4*)(ep + (size_t)(fr - 12) * NUP + co) = U[3];
; #pragma unroll
;                     for (int m = 0; m < 4; ++m) { const f32x4 sp = (fr == 15 && m > 0) ? U[m > 0 ? m - 1 : 0] : U[m]; const f32x4 sn = (fr == 0 && m < 3) ? U[m < 3 ? m + 1 : 3] : U[m];
;                         f32x4 pv, nv;
; #pragma unroll
;                         for (int j = 0; j < 4; ++j) { pv[j] = __int_as_float(__builtin_amdgcn_update_dpp(0, __float_as_int(sp[j]), 0x121, 0xf, 0xf, false)); nv[j] = __int_as_float(__builtin_amdgcn_update_dpp(0, __float_as_int(sn[j]), 0x12F, 0xf, 0xf, false)); }
;                         const f32x4 R = prm[bj][1] * pv + prm[bj][2] * U[m] + prm[bj][3] * nv + prm[bj][4];
;                         if (bj == 1) {
; #pragma unroll
;                             for (int j = 0; j < 4; ++j) SG[m][j] = R[j] * __builtin_amdgcn_rcpf(1.0f + __expf(-R[j])); }
;                         else { const int r = row0 + ai * HALF + m * 16; const bool skip = (m == 0 && fr == 0) || (m == 3 && fr == 15);
;                             const f32x4 o = R * SG[m]; u32x2 w; w.x = cvt_pk_bf16_asm(o[0], o[1]); w.y = cvt_pk_bf16_asm(o[2], o[3]);
;                             if (!skip) *(u32x2*)(act + (size_t)r * FFD + u.pn * 128 + wc * 32 + 8 * fq + 4 * n) = w; } } } }
	v_pk_fma_f32 v[18:19], v[18:19], v[230:231], v[204:205] op_sel_hi:[1,0,1]
	v_pk_fma_f32 v[20:21], v[20:21], v[230:231], v[206:207] op_sel_hi:[1,0,1]
	v_pk_fma_f32 v[22:23], v[22:23], v[230:231], v[204:205] op_sel:[0,1,0] op_sel_hi:[1,1,1]
	v_pk_fma_f32 v[24:25], v[24:25], v[230:231], v[206:207] op_sel:[0,1,0] op_sel_hi:[1,1,1]
	s_mov_b64 exec, s[4:5]
	global_store_dwordx4 v244, v[30:33], s[54:55] offset:528
	s_add_u32 s16, s54, 0x5800
	s_addc_u32 s17, s55, 0
	global_store_dwordx4 v244, v[26:29], s[16:17] offset:528
	s_mov_b64 exec, s[6:7]
	s_add_u32 s56, s54, 0xb000
	s_addc_u32 s57, s55, 0
	global_store_dwordx4 v244, v[18:21], s[56:57] offset:528
	s_add_u32 s16, s54, 0x10800
	s_addc_u32 s17, s55, 0
	global_store_dwordx4 v244, v[22:25], s[16:17] offset:528
	s_mov_b64 exec, -1
	v_pk_fma_f32 v[232:233], v[212:213], v[30:31], v[220:221]
	v_pk_fma_f32 v[234:235], v[212:213], v[26:27], v[220:221]
	v_pk_fma_f32 v[236:237], v[212:213], v[18:19], v[220:221]
	v_pk_fma_f32 v[238:239], v[212:213], v[22:23], v[220:221]
	v_pk_fma_f32 v[234:235], v[208:209], v[30:31], v[234:235]
	v_pk_fma_f32 v[236:237], v[208:209], v[26:27], v[236:237]
	v_pk_fma_f32 v[238:239], v[208:209], v[18:19], v[238:239]
	v_pk_fma_f32 v[232:233], v[216:217], v[26:27], v[232:233]
	v_pk_fma_f32 v[234:235], v[216:217], v[18:19], v[234:235]
	v_pk_fma_f32 v[236:237], v[216:217], v[22:23], v[236:237]
	v_fmac_f32_dpp v232, v22, v208 row_ror:1 row_mask:0xf bank_mask:0xf
	v_fmac_f32_dpp v233, v23, v209 row_ror:1 row_mask:0xf bank_mask:0xf
	v_fmac_f32_dpp v238, v30, v216 row_ror:15 row_mask:0xf bank_mask:0xf
	v_fmac_f32_dpp v239, v31, v217 row_ror:15 row_mask:0xf bank_mask:0xf
	v_pk_mul_f32 v[30:31], v[232:233], v[240:241]
	v_pk_mul_f32 v[26:27], v[234:235], v[240:241]
	v_pk_mul_f32 v[18:19], v[236:237], v[240:241]
	v_pk_mul_f32 v[22:23], v[238:239], v[240:241]
	v_exp_f32_e32 v30, v30
	v_exp_f32_e32 v31, v31
	v_exp_f32_e32 v26, v26
	v_exp_f32_e32 v27, v27
	v_exp_f32_e32 v18, v18
	v_exp_f32_e32 v19, v19
	v_exp_f32_e32 v22, v22
	v_exp_f32_e32 v23, v23
	v_add_f32_e32 v30, 1.0, v30
	v_add_f32_e32 v31, 1.0, v31
	v_add_f32_e32 v26, 1.0, v26
	v_add_f32_e32 v27, 1.0, v27
	v_add_f32_e32 v18, 1.0, v18
	v_add_f32_e32 v19, 1.0, v19
	v_add_f32_e32 v22, 1.0, v22
	v_add_f32_e32 v23, 1.0, v23
	v_rcp_f32_e32 v30, v30
	v_rcp_f32_e32 v31, v31
	v_rcp_f32_e32 v26, v26
	v_rcp_f32_e32 v27, v27
	v_rcp_f32_e32 v18, v18
	v_rcp_f32_e32 v19, v19
	v_rcp_f32_e32 v22, v22
	v_rcp_f32_e32 v23, v23
	v_pk_mul_f32 v[30:31], v[232:233], v[30:31]
	v_pk_mul_f32 v[26:27], v[234:235], v[26:27]
	v_pk_mul_f32 v[18:19], v[236:237], v[18:19]
	v_pk_mul_f32 v[22:23], v[238:239], v[22:23]
	v_pk_fma_f32 v[232:233], v[214:215], v[32:33], v[222:223]
	v_pk_fma_f32 v[234:235], v[214:215], v[28:29], v[222:223]
	v_pk_fma_f32 v[236:237], v[214:215], v[20:21], v[222:223]
	v_pk_fma_f32 v[238:239], v[214:215], v[24:25], v[222:223]
	v_pk_fma_f32 v[234:235], v[210:211], v[32:33], v[234:235]
	v_pk_fma_f32 v[236:237], v[210:211], v[28:29], v[236:237]
	v_pk_fma_f32 v[238:239], v[210:211], v[20:21], v[238:239]
	v_pk_fma_f32 v[232:233], v[218:219], v[28:29], v[232:233]
	v_pk_fma_f32 v[234:235], v[218:219], v[20:21], v[234:235]
	v_pk_fma_f32 v[236:237], v[218:219], v[24:25], v[236:237]
	v_fmac_f32_dpp v232, v24, v210 row_ror:1 row_mask:0xf bank_mask:0xf
	v_fmac_f32_dpp v233, v25, v211 row_ror:1 row_mask:0xf bank_mask:0xf
	v_fmac_f32_dpp v238, v32, v218 row_ror:15 row_mask:0xf bank_mask:0xf
	v_fmac_f32_dpp v239, v33, v219 row_ror:15 row_mask:0xf bank_mask:0xf
	v_pk_mul_f32 v[32:33], v[232:233], v[240:241]
	v_pk_mul_f32 v[28:29], v[234:235], v[240:241]
	v_pk_mul_f32 v[20:21], v[236:237], v[240:241]
	v_pk_mul_f32 v[24:25], v[238:239], v[240:241]
	v_exp_f32_e32 v32, v32
	v_exp_f32_e32 v33, v33
	v_exp_f32_e32 v28, v28
	v_exp_f32_e32 v29, v29
	v_exp_f32_e32 v20, v20
	v_exp_f32_e32 v21, v21
	v_exp_f32_e32 v24, v24
	v_exp_f32_e32 v25, v25
	v_add_f32_e32 v32, 1.0, v32
	v_add_f32_e32 v33, 1.0, v33
	v_add_f32_e32 v28, 1.0, v28
	v_add_f32_e32 v29, 1.0, v29
	v_add_f32_e32 v20, 1.0, v20
	v_add_f32_e32 v21, 1.0, v21
	v_add_f32_e32 v24, 1.0, v24
	v_add_f32_e32 v25, 1.0, v25
	v_rcp_f32_e32 v32, v32
	v_rcp_f32_e32 v33, v33
	v_rcp_f32_e32 v28, v28
	v_rcp_f32_e32 v29, v29
	v_rcp_f32_e32 v20, v20
; __device__ __forceinline__ unsigned cvt_pk_bf16_asm(float lo, float hi) { unsigned r; asm volatile("v_cvt_pk_bf16_f32 %0, %1, %2" : "=v"(r) : "v"(lo), "v"(hi)); return r; }
;     __device__ __forceinline__ void operator()(const f32x4 (&acc)[2][2][4][2], const Unit& u, int wr, int wc, int fr, int fq) const {
;     ...
;             for (int ai = 0; ai < 2; ++ai) {
;                 float* ep = edge + (size_t)(u.pm * 4 + ai * 2 + wr) * 4 * NUP + colt;
;                 f32x4 SG[4];
; #pragma unroll
;                 for (int bjr = 0; bjr < 2; ++bjr) { const int bj = 1 - bjr; const int co = bj * HALF + 4 * n;
;                     f32x4 U[4];
; #pragma unroll
;                     for (int m = 0; m < 4; ++m) U[m] = acc[ai][bj][m][n] * rs[ai][m] + prm[bj][0];
;                     if (fr < 2) *(f32x4*)(ep + (size_t)fr * NUP + co) = U[0];
;                     if (fr >= 14) *(f32x4*)(ep + (size_t)(fr - 12) * NUP + co) = U[3];
; #pragma unroll
;                     for (int m = 0; m < 4; ++m) { const f32x4 sp = (fr == 15 && m > 0) ? U[m > 0 ? m - 1 : 0] : U[m]; const f32x4 sn = (fr == 0 && m < 3) ? U[m < 3 ? m + 1 : 3] : U[m];
;                         f32x4 pv, nv;
; #pragma unroll
;                         for (int j = 0; j < 4; ++j) { pv[j] = __int_as_float(__builtin_amdgcn_update_dpp(0, __float_as_int(sp[j]), 0x121, 0xf, 0xf, false)); nv[j] = __int_as_float(__builtin_amdgcn_update_dpp(0, __float_as_int(sn[j]), 0x12F, 0xf, 0xf, false)); }
;                         const f32x4 R = prm[bj][1] * pv + prm[bj][2] * U[m] + prm[bj][3] * nv + prm[bj][4];
;                         if (bj == 1) {
; #pragma unroll
;                             for (int j = 0; j < 4; ++j) SG[m][j] = R[j] * __builtin_amdgcn_rcpf(1.0f + __expf(-R[j])); }
;                         else { const int r = row0 + ai * HALF + m * 16; const bool skip = (m == 0 && fr == 0) || (m == 3 && fr == 15);
;                             const f32x4 o = R * SG[m]; u32x2 w; w.x = cvt_pk_bf16_asm(o[0], o[1]); w.y = cvt_pk_bf16_asm(o[2], o[3]);
;                             if (!skip) *(u32x2*)(act + (size_t)r * FFD + u.pn * 128 + wc * 32 + 8 * fq + 4 * n) = w; } } } }
	v_rcp_f32_e32 v21, v21
	v_rcp_f32_e32 v24, v24
	v_rcp_f32_e32 v25, v25
	v_pk_mul_f32 v[32:33], v[232:233], v[32:33]
	v_pk_mul_f32 v[28:29], v[234:235], v[28:29]
	v_pk_mul_f32 v[20:21], v[236:237], v[20:21]
	v_pk_mul_f32 v[24:25], v[238:239], v[24:25]
	v_pk_fma_f32 v[14:15], v[14:15], v[228:229], v[184:185] op_sel_hi:[1,0,1]
	v_pk_fma_f32 v[16:17], v[16:17], v[228:229], v[186:187] op_sel_hi:[1,0,1]
	v_pk_fma_f32 v[6:7], v[6:7], v[228:229], v[184:185] op_sel:[0,1,0] op_sel_hi:[1,1,1]
	v_pk_fma_f32 v[8:9], v[8:9], v[228:229], v[186:187] op_sel:[0,1,0] op_sel_hi:[1,1,1]
	v_pk_fma_f32 v[2:3], v[2:3], v[230:231], v[184:185] op_sel_hi:[1,0,1]
	v_pk_fma_f32 v[4:5], v[4:5], v[230:231], v[186:187] op_sel_hi:[1,0,1]
	v_pk_fma_f32 v[10:11], v[10:11], v[230:231], v[184:185] op_sel:[0,1,0] op_sel_hi:[1,1,1]
	v_pk_fma_f32 v[12:13], v[12:13], v[230:231], v[186:187] op_sel:[0,1,0] op_sel_hi:[1,1,1]
	s_mov_b64 exec, s[4:5]
	global_store_dwordx4 v244, v[14:17], s[54:55] offset:16
	s_add_u32 s16, s54, 0x5800
	s_addc_u32 s17, s55, 0
	global_store_dwordx4 v244, v[6:9], s[16:17] offset:16
	s_mov_b64 exec, s[6:7]
	s_add_u32 s56, s54, 0xb000
	s_addc_u32 s57, s55, 0
	global_store_dwordx4 v244, v[2:5], s[56:57] offset:16
	s_add_u32 s16, s54, 0x10800
	s_addc_u32 s17, s55, 0
	global_store_dwordx4 v244, v[10:13], s[16:17] offset:16
	s_mov_b64 exec, -1
	v_pk_fma_f32 v[232:233], v[192:193], v[14:15], v[200:201]
	v_pk_fma_f32 v[234:235], v[192:193], v[6:7], v[200:201]
	v_pk_fma_f32 v[236:237], v[192:193], v[2:3], v[200:201]
	v_pk_fma_f32 v[238:239], v[192:193], v[10:11], v[200:201]
	v_pk_fma_f32 v[234:235], v[188:189], v[14:15], v[234:235]
	v_pk_fma_f32 v[236:237], v[188:189], v[6:7], v[236:237]
	v_pk_fma_f32 v[238:239], v[188:189], v[2:3], v[238:239]
	v_pk_fma_f32 v[232:233], v[196:197], v[6:7], v[232:233]
	v_pk_fma_f32 v[234:235], v[196:197], v[2:3], v[234:235]
	v_pk_fma_f32 v[236:237], v[196:197], v[10:11], v[236:237]
	v_fmac_f32_dpp v232, v10, v188 row_ror:1 row_mask:0xf bank_mask:0xf
	v_fmac_f32_dpp v233, v11, v189 row_ror:1 row_mask:0xf bank_mask:0xf
	v_fmac_f32_dpp v238, v14, v196 row_ror:15 row_mask:0xf bank_mask:0xf
	v_fmac_f32_dpp v239, v15, v197 row_ror:15 row_mask:0xf bank_mask:0xf
	v_pk_mul_f32 v[232:233], v[232:233], v[30:31]
	v_pk_mul_f32 v[234:235], v[234:235], v[26:27]
	v_pk_mul_f32 v[236:237], v[236:237], v[18:19]
	v_pk_mul_f32 v[238:239], v[238:239], v[22:23]
	v_cvt_pk_bf16_f32 v80, v232, v233
	v_cvt_pk_bf16_f32 v72, v234, v235
	v_cvt_pk_bf16_f32 v68, v236, v237
	v_cvt_pk_bf16_f32 v76, v238, v239
	v_pk_fma_f32 v[232:233], v[194:195], v[16:17], v[202:203]
	v_pk_fma_f32 v[234:235], v[194:195], v[8:9], v[202:203]
	v_pk_fma_f32 v[236:237], v[194:195], v[4:5], v[202:203]
	v_pk_fma_f32 v[238:239], v[194:195], v[12:13], v[202:203]
	v_pk_fma_f32 v[234:235], v[190:191], v[16:17], v[234:235]
	v_pk_fma_f32 v[236:237], v[190:191], v[8:9], v[236:237]
	v_pk_fma_f32 v[238:239], v[190:191], v[4:5], v[238:239]
	v_pk_fma_f32 v[232:233], v[198:199], v[8:9], v[232:233]
	v_pk_fma_f32 v[234:235], v[198:199], v[4:5], v[234:235]
	v_pk_fma_f32 v[236:237], v[198:199], v[12:13], v[236:237]
	v_fmac_f32_dpp v232, v12, v190 row_ror:1 row_mask:0xf bank_mask:0xf
	v_fmac_f32_dpp v233, v13, v191 row_ror:1 row_mask:0xf bank_mask:0xf
	v_fmac_f32_dpp v238, v16, v198 row_ror:15 row_mask:0xf bank_mask:0xf
	v_fmac_f32_dpp v239, v17, v199 row_ror:15 row_mask:0xf bank_mask:0xf
	v_pk_mul_f32 v[232:233], v[232:233], v[32:33]
	v_pk_mul_f32 v[234:235], v[234:235], v[28:29]
	v_pk_mul_f32 v[236:237], v[236:237], v[20:21]
	v_pk_mul_f32 v[238:239], v[238:239], v[24:25]
	v_cvt_pk_bf16_f32 v81, v232, v233
	v_cvt_pk_bf16_f32 v73, v234, v235
	v_cvt_pk_bf16_f32 v69, v236, v237
	v_cvt_pk_bf16_f32 v77, v238, v239
	s_add_u32 s16, s74, 0xb0000
	s_addc_u32 s17, s75, 0
	s_not_b64 exec, s[4:5]
	global_store_dwordx4 v245, v[78:81], s[16:17]
	s_mov_b64 exec, -1
	s_add_u32 s16, s74, 0xb1600
	s_addc_u32 s17, s75, 0
	global_store_dwordx4 v245, v[70:73], s[16:17]
	s_add_u32 s16, s74, 0xb2c00
	s_addc_u32 s17, s75, 0
	global_store_dwordx4 v245, v[66:69], s[16:17]
	s_add_u32 s16, s74, 0xb4200
	s_addc_u32 s17, s75, 0
	s_not_b64 exec, s[6:7]
	global_store_dwordx4 v245, v[74:77], s[16:17]
	s_mov_b64 exec, -1
	s_branch .LBB0_451
